# weight-conversion bf16 stores made write-through (sc1) so they do not sit dirty in L2
# speedup vs baseline: 1.0026x; 1.0026x over previous
; #define GAS __attribute__((address_space(1)))
; #define LAS __attribute__((address_space(3)))
; #define LDS_WAIT() asm volatile("s_waitcnt lgkmcnt(0)" ::: "memory")
; DI unsigned pk2(float lo, float hi) { f32x2 v = {lo, hi}; bf16x2_t b = __builtin_convertvector(v, bf16x2_t); return __builtin_bit_cast(unsigned, b); }
;     ...
;         LAS float* w = scr + (lane >> 4) * 65 + 4 * (lane & 15);
; #pragma unroll
;         for (int i = 0; i < 16; ++i) { w[(4 * i) * 65 + 0] = v[i].x; w[(4 * i) * 65 + 1] = v[i].y; w[(4 * i) * 65 + 2] = v[i].z; w[(4 * i) * 65 + 3] = v[i].w; }
;     }
;     LDS_WAIT(); asm volatile("" ::: "memory");
;     const int c = lane & 7;
;     const f32x4 s0 = sc[0], s1 = sc[1];
; #pragma unroll
;     for (int j = 0; j < 8; ++j) {
;         const int nn = (lane >> 3) + 8 * j; const LAS float* s = scr + (8 * c) * 65 + nn;
;         v4u o; o.x = pk2(s[0 * 65] * s0.x, s[1 * 65] * s0.y); o.y = pk2(s[2 * 65] * s0.z, s[3 * 65] * s0.w); o.z = pk2(s[4 * 65] * s1.x, s[5 * 65] * s1.y); o.w = pk2(s[6 * 65] * s1.z, s[7 * 65] * s1.w);
;         if (!(variant & 4)) *(GAS v4u*)(t.dst + (size_t)(t.drow0 + nn) * t.Kd + t.k0 + 8 * c) = o;
;         else asm volatile("" :: "v"(o));
;     }
;     LDS_WAIT(); asm volatile("" ::: "memory");
.LBB0_51:
	ds_write2_b32 v163, v84, v85 offset1:1
	ds_write2_b32 v163, v86, v87 offset0:2 offset1:3
	ds_write2_b32 v174, v92, v93 offset1:1
	ds_write2_b32 v175, v94, v95 offset1:1
	ds_write2_b32 v176, v96, v97 offset1:1
	ds_write2_b32 v177, v98, v99 offset1:1
	ds_write2_b32 v178, v100, v101 offset1:1
	ds_write2_b32 v179, v102, v103 offset1:1
	ds_write2_b32 v180, v104, v105 offset1:1
	ds_write2_b32 v181, v106, v107 offset1:1
	ds_write2_b32 v182, v108, v109 offset1:1
	ds_write2_b32 v183, v110, v111 offset1:1
	ds_write2_b32 v184, v112, v113 offset1:1
	ds_write2_b32 v185, v114, v115 offset1:1
	ds_write2_b32 v186, v116, v117 offset1:1
	ds_write2_b32 v187, v118, v119 offset1:1
	ds_write2_b32 v188, v120, v121 offset1:1
	ds_write2_b32 v189, v122, v123 offset1:1
	ds_write2_b32 v190, v124, v125 offset1:1
	ds_write2_b32 v191, v126, v127 offset1:1
	ds_write2_b32 v192, v128, v129 offset1:1
	ds_write2_b32 v193, v130, v131 offset1:1
	ds_write2_b32 v194, v132, v133 offset1:1
	ds_write2_b32 v195, v134, v135 offset1:1
	ds_write2_b32 v196, v136, v137 offset1:1
	ds_write2_b32 v197, v138, v139 offset1:1
	ds_write2_b32 v198, v144, v145 offset1:1
	ds_write2_b32 v199, v146, v147 offset1:1
	ds_write2_b32 v200, v140, v141 offset1:1
	ds_write2_b32 v201, v142, v143 offset1:1
	ds_write2_b32 v202, v148, v149 offset1:1
	ds_write2_b32 v203, v150, v151 offset1:1
	s_waitcnt lgkmcnt(0)
	ds_read2_b32 v[2:3], v165 offset1:8
	ds_read2_b32 v[6:7], v165 offset0:65 offset1:73
	ds_read2_b32 v[178:179], v165 offset0:130 offset1:138
	ds_read2_b32 v[180:181], v165 offset0:195 offset1:203
	ds_read2_b32 v[182:183], v173 offset0:4 offset1:12
	ds_read2_b32 v[184:185], v173 offset0:69 offset1:77
	ds_read2_b32 v[186:187], v173 offset0:134 offset1:142
	ds_read2_b32 v[188:189], v173 offset0:199 offset1:207
	s_waitcnt lgkmcnt(7)
	v_mov_b32_e32 v174, v2
	s_waitcnt lgkmcnt(6)
	v_mov_b32_e32 v175, v6
	s_waitcnt lgkmcnt(5)
	v_mov_b32_e32 v176, v178
	s_waitcnt lgkmcnt(4)
	v_mov_b32_e32 v177, v180
	v_pk_mul_f32 v[174:175], v[72:73], v[174:175]
	v_pk_mul_f32 v[176:177], v[74:75], v[176:177]
	v_cvt_pk_bf16_f32 v174, v174, v175
	v_cvt_pk_bf16_f32 v175, v176, v177
	s_waitcnt lgkmcnt(3)
	v_mov_b32_e32 v176, v182
	s_waitcnt lgkmcnt(2)
	v_mov_b32_e32 v177, v184
	s_waitcnt lgkmcnt(1)
	v_mov_b32_e32 v190, v186
	s_waitcnt lgkmcnt(0)
	v_mov_b32_e32 v191, v188
	v_pk_mul_f32 v[176:177], v[64:65], v[176:177]
	v_pk_mul_f32 v[190:191], v[66:67], v[190:191]
	v_add_u32_e32 v1, s56, v164
	v_cvt_pk_bf16_f32 v176, v176, v177
	v_cvt_pk_bf16_f32 v177, v190, v191
	v_mad_i64_i32 v[190:191], s[28:29], s57, v1, 0
	s_ashr_i32 s25, s24, 31
	v_lshl_add_u64 v[190:191], v[190:191], 1, v[160:161]
	s_lshl_b64 s[28:29], s[24:25], 1
	v_lshl_add_u64 v[190:191], v[190:191], 0, s[28:29]
	v_mov_b32_e32 v159, v0
	v_mov_b32_e32 v6, v3
	v_lshl_add_u64 v[190:191], v[190:191], 0, v[158:159]
	v_pk_mul_f32 v[2:3], v[72:73], v[6:7]
	v_mov_b32_e32 v180, v179
	global_store_dwordx4 v[190:191], v[174:177], off sc1
	v_mov_b32_e32 v184, v183
	v_mov_b32_e32 v188, v187
	v_cvt_pk_bf16_f32 v174, v2, v3
	v_pk_mul_f32 v[2:3], v[74:75], v[180:181]
	v_add_u32_e32 v1, s56, v166
	v_cvt_pk_bf16_f32 v175, v2, v3
	v_pk_mul_f32 v[2:3], v[64:65], v[184:185]
	ds_read2_b32 v[6:7], v165 offset0:16 offset1:24
	v_cvt_pk_bf16_f32 v176, v2, v3
	v_pk_mul_f32 v[2:3], v[66:67], v[188:189]
	ds_read2_b32 v[178:179], v165 offset0:81 offset1:89
	v_cvt_pk_bf16_f32 v177, v2, v3
	v_mad_i64_i32 v[2:3], s[30:31], s57, v1, 0
	v_lshl_add_u64 v[2:3], v[2:3], 1, v[160:161]
	ds_read2_b32 v[180:181], v165 offset0:146 offset1:154
	ds_read2_b32 v[182:183], v165 offset0:211 offset1:219
	v_lshl_add_u64 v[2:3], v[2:3], 0, s[28:29]
	v_lshl_add_u64 v[2:3], v[2:3], 0, v[158:159]
	ds_read2_b32 v[184:185], v173 offset0:20 offset1:28
	ds_read2_b32 v[186:187], v173 offset0:85 offset1:93
	global_store_dwordx4 v[2:3], v[174:177], off sc1
	s_waitcnt lgkmcnt(5)
	v_mov_b32_e32 v2, v6
	s_waitcnt lgkmcnt(4)
	v_mov_b32_e32 v3, v178
	v_pk_mul_f32 v[2:3], v[72:73], v[2:3]
	ds_read2_b32 v[188:189], v173 offset0:150 offset1:158
	ds_read2_b32 v[190:191], v173 offset0:215 offset1:223
	v_cvt_pk_bf16_f32 v174, v2, v3
	s_waitcnt lgkmcnt(5)
	v_mov_b32_e32 v2, v180
	s_waitcnt lgkmcnt(4)
	v_mov_b32_e32 v3, v182
	v_pk_mul_f32 v[2:3], v[74:75], v[2:3]
	v_add_u32_e32 v1, s56, v167
	v_cvt_pk_bf16_f32 v175, v2, v3
	s_waitcnt lgkmcnt(3)
	v_mov_b32_e32 v2, v184
	s_waitcnt lgkmcnt(2)
	v_mov_b32_e32 v3, v186
	v_pk_mul_f32 v[2:3], v[64:65], v[2:3]
	v_mov_b32_e32 v178, v7
	v_cvt_pk_bf16_f32 v176, v2, v3
	s_waitcnt lgkmcnt(1)
	v_mov_b32_e32 v2, v188
	s_waitcnt lgkmcnt(0)
; #define GAS __attribute__((address_space(1)))
; #define LAS __attribute__((address_space(3)))
; #define LDS_WAIT() asm volatile("s_waitcnt lgkmcnt(0)" ::: "memory")
; DI unsigned pk2(float lo, float hi) { f32x2 v = {lo, hi}; bf16x2_t b = __builtin_convertvector(v, bf16x2_t); return __builtin_bit_cast(unsigned, b); }
;     ...
;     for (int j = 0; j < 8; ++j) {
;         const int nn = (lane >> 3) + 8 * j; const LAS float* s = scr + (8 * c) * 65 + nn;
;         v4u o; o.x = pk2(s[0 * 65] * s0.x, s[1 * 65] * s0.y); o.y = pk2(s[2 * 65] * s0.z, s[3 * 65] * s0.w); o.z = pk2(s[4 * 65] * s1.x, s[5 * 65] * s1.y); o.w = pk2(s[6 * 65] * s1.z, s[7 * 65] * s1.w);
;         if (!(variant & 4)) *(GAS v4u*)(t.dst + (size_t)(t.drow0 + nn) * t.Kd + t.k0 + 8 * c) = o;
;         else asm volatile("" :: "v"(o));
;     }
;     LDS_WAIT(); asm volatile("" ::: "memory");
	v_mov_b32_e32 v3, v190
	v_pk_mul_f32 v[2:3], v[66:67], v[2:3]
	v_mov_b32_e32 v182, v181
	v_cvt_pk_bf16_f32 v177, v2, v3
	v_mad_i64_i32 v[2:3], s[30:31], s57, v1, 0
	v_lshl_add_u64 v[2:3], v[2:3], 1, v[160:161]
	v_lshl_add_u64 v[2:3], v[2:3], 0, s[28:29]
	v_lshl_add_u64 v[2:3], v[2:3], 0, v[158:159]
	global_store_dwordx4 v[2:3], v[174:177], off sc1
	v_pk_mul_f32 v[2:3], v[72:73], v[178:179]
	v_mov_b32_e32 v186, v185
	v_cvt_pk_bf16_f32 v174, v2, v3
	v_pk_mul_f32 v[2:3], v[74:75], v[182:183]
	v_mov_b32_e32 v190, v189
	v_cvt_pk_bf16_f32 v175, v2, v3
	v_pk_mul_f32 v[2:3], v[64:65], v[186:187]
	v_add_u32_e32 v1, s56, v168
	v_cvt_pk_bf16_f32 v176, v2, v3
	v_pk_mul_f32 v[2:3], v[66:67], v[190:191]
	ds_read2_b32 v[6:7], v165 offset0:32 offset1:40
	ds_read2_b32 v[178:179], v165 offset0:97 offset1:105
	v_cvt_pk_bf16_f32 v177, v2, v3
	v_mad_i64_i32 v[2:3], s[30:31], s57, v1, 0
	v_lshl_add_u64 v[2:3], v[2:3], 1, v[160:161]
	ds_read2_b32 v[180:181], v165 offset0:162 offset1:170
	ds_read2_b32 v[182:183], v165 offset0:227 offset1:235
	v_lshl_add_u64 v[2:3], v[2:3], 0, s[28:29]
	v_lshl_add_u64 v[2:3], v[2:3], 0, v[158:159]
	ds_read2_b32 v[184:185], v173 offset0:36 offset1:44
	ds_read2_b32 v[186:187], v173 offset0:101 offset1:109
	global_store_dwordx4 v[2:3], v[174:177], off sc1
	s_waitcnt lgkmcnt(5)
	v_mov_b32_e32 v2, v6
	s_waitcnt lgkmcnt(4)
	v_mov_b32_e32 v3, v178
	v_pk_mul_f32 v[2:3], v[72:73], v[2:3]
	ds_read2_b32 v[188:189], v173 offset0:166 offset1:174
	ds_read2_b32 v[190:191], v173 offset0:231 offset1:239
	v_cvt_pk_bf16_f32 v174, v2, v3
	s_waitcnt lgkmcnt(5)
	v_mov_b32_e32 v2, v180
	s_waitcnt lgkmcnt(4)
	v_mov_b32_e32 v3, v182
	v_pk_mul_f32 v[2:3], v[74:75], v[2:3]
	v_add_u32_e32 v1, s56, v169
	v_cvt_pk_bf16_f32 v175, v2, v3
	s_waitcnt lgkmcnt(3)
	v_mov_b32_e32 v2, v184
	s_waitcnt lgkmcnt(2)
	v_mov_b32_e32 v3, v186
	v_pk_mul_f32 v[2:3], v[64:65], v[2:3]
	v_mov_b32_e32 v178, v7
	v_cvt_pk_bf16_f32 v176, v2, v3
	s_waitcnt lgkmcnt(1)
	v_mov_b32_e32 v2, v188
	s_waitcnt lgkmcnt(0)
	v_mov_b32_e32 v3, v190
	v_pk_mul_f32 v[2:3], v[66:67], v[2:3]
	v_mov_b32_e32 v182, v181
	v_cvt_pk_bf16_f32 v177, v2, v3
	v_mad_i64_i32 v[2:3], s[30:31], s57, v1, 0
	v_lshl_add_u64 v[2:3], v[2:3], 1, v[160:161]
	v_lshl_add_u64 v[2:3], v[2:3], 0, s[28:29]
	v_lshl_add_u64 v[2:3], v[2:3], 0, v[158:159]
	global_store_dwordx4 v[2:3], v[174:177], off sc1
	v_pk_mul_f32 v[2:3], v[72:73], v[178:179]
	v_mov_b32_e32 v186, v185
	v_cvt_pk_bf16_f32 v174, v2, v3
	v_pk_mul_f32 v[2:3], v[74:75], v[182:183]
	v_mov_b32_e32 v190, v189
	v_cvt_pk_bf16_f32 v175, v2, v3
	v_pk_mul_f32 v[2:3], v[64:65], v[186:187]
	v_add_u32_e32 v1, s56, v170
	v_cvt_pk_bf16_f32 v176, v2, v3
	v_pk_mul_f32 v[2:3], v[66:67], v[190:191]
	ds_read2_b32 v[6:7], v165 offset0:48 offset1:56
	ds_read2_b32 v[178:179], v165 offset0:113 offset1:121
	v_cvt_pk_bf16_f32 v177, v2, v3
	v_mad_i64_i32 v[2:3], s[30:31], s57, v1, 0
	v_lshl_add_u64 v[2:3], v[2:3], 1, v[160:161]
	ds_read2_b32 v[180:181], v165 offset0:178 offset1:186
	ds_read2_b32 v[182:183], v165 offset0:243 offset1:251
	v_lshl_add_u64 v[2:3], v[2:3], 0, s[28:29]
	v_lshl_add_u64 v[2:3], v[2:3], 0, v[158:159]
	ds_read2_b32 v[184:185], v173 offset0:52 offset1:60
	ds_read2_b32 v[186:187], v173 offset0:117 offset1:125
	global_store_dwordx4 v[2:3], v[174:177], off sc1
	s_waitcnt lgkmcnt(5)
	v_mov_b32_e32 v2, v6
	s_waitcnt lgkmcnt(4)
	v_mov_b32_e32 v3, v178
	v_pk_mul_f32 v[2:3], v[72:73], v[2:3]
	ds_read2_b32 v[188:189], v173 offset0:182 offset1:190
	ds_read2_b32 v[190:191], v173 offset0:247 offset1:255
	v_cvt_pk_bf16_f32 v174, v2, v3
	s_waitcnt lgkmcnt(5)
	v_mov_b32_e32 v2, v180
	s_waitcnt lgkmcnt(4)
	v_mov_b32_e32 v3, v182
	v_pk_mul_f32 v[2:3], v[74:75], v[2:3]
	v_add_u32_e32 v1, s56, v171
	v_cvt_pk_bf16_f32 v175, v2, v3
	s_waitcnt lgkmcnt(3)
	v_mov_b32_e32 v2, v184
	s_waitcnt lgkmcnt(2)
	v_mov_b32_e32 v3, v186
	v_pk_mul_f32 v[2:3], v[64:65], v[2:3]
	v_mov_b32_e32 v178, v7
	v_cvt_pk_bf16_f32 v176, v2, v3
	s_waitcnt lgkmcnt(1)
	v_mov_b32_e32 v2, v188
	s_waitcnt lgkmcnt(0)
	v_mov_b32_e32 v3, v190
	v_pk_mul_f32 v[2:3], v[66:67], v[2:3]
	v_mov_b32_e32 v182, v181
	v_cvt_pk_bf16_f32 v177, v2, v3
	v_mad_i64_i32 v[2:3], s[30:31], s57, v1, 0
	v_lshl_add_u64 v[2:3], v[2:3], 1, v[160:161]
	v_lshl_add_u64 v[2:3], v[2:3], 0, s[28:29]
	v_lshl_add_u64 v[2:3], v[2:3], 0, v[158:159]
	global_store_dwordx4 v[2:3], v[174:177], off sc1
	v_pk_mul_f32 v[2:3], v[72:73], v[178:179]
	v_mov_b32_e32 v186, v185
	v_cvt_pk_bf16_f32 v174, v2, v3
	v_pk_mul_f32 v[2:3], v[74:75], v[182:183]
	v_mov_b32_e32 v190, v189
	v_cvt_pk_bf16_f32 v175, v2, v3
	v_pk_mul_f32 v[2:3], v[64:65], v[186:187]
	v_add_u32_e32 v1, s56, v172
	v_cvt_pk_bf16_f32 v176, v2, v3
	v_pk_mul_f32 v[2:3], v[66:67], v[190:191]
	s_nop 0
	v_cvt_pk_bf16_f32 v177, v2, v3
	v_mad_i64_i32 v[2:3], s[30:31], s57, v1, 0
	v_lshl_add_u64 v[2:3], v[2:3], 1, v[160:161]
	v_lshl_add_u64 v[2:3], v[2:3], 0, s[28:29]
	v_lshl_add_u64 v[2:3], v[2:3], 0, v[158:159]
	global_store_dwordx4 v[2:3], v[174:177], off sc1
	s_waitcnt lgkmcnt(0)

; #define GAS __attribute__((address_space(1)))
; #define LAS __attribute__((address_space(3)))
; #define LDS_WAIT() asm volatile("s_waitcnt lgkmcnt(0)" ::: "memory")
; DI unsigned pk2(float lo, float hi) { f32x2 v = {lo, hi}; bf16x2_t b = __builtin_convertvector(v, bf16x2_t); return __builtin_bit_cast(unsigned, b); }
;     ...
;         LAS float* w = scr + (lane >> 4) * 65 + 4 * (lane & 15);
; #pragma unroll
;         for (int i = 0; i < 16; ++i) { w[(4 * i) * 65 + 0] = v[i].x; w[(4 * i) * 65 + 1] = v[i].y; w[(4 * i) * 65 + 2] = v[i].z; w[(4 * i) * 65 + 3] = v[i].w; }
;     }
;     LDS_WAIT(); asm volatile("" ::: "memory");
;     const int c = lane & 7;
;     const f32x4 s0 = sc[0], s1 = sc[1];
; #pragma unroll
;     for (int j = 0; j < 8; ++j) {
;         const int nn = (lane >> 3) + 8 * j; const LAS float* s = scr + (8 * c) * 65 + nn;
;         v4u o; o.x = pk2(s[0 * 65] * s0.x, s[1 * 65] * s0.y); o.y = pk2(s[2 * 65] * s0.z, s[3 * 65] * s0.w); o.z = pk2(s[4 * 65] * s1.x, s[5 * 65] * s1.y); o.w = pk2(s[6 * 65] * s1.z, s[7 * 65] * s1.w);
;         if (!(variant & 4)) *(GAS v4u*)(t.dst + (size_t)(t.drow0 + nn) * t.Kd + t.k0 + 8 * c) = o;
;         else asm volatile("" :: "v"(o));
;     }
;     LDS_WAIT(); asm volatile("" ::: "memory");
.LBB0_89:
	v_add_u32_e32 v174, 0x410, v163
	v_add_u32_e32 v175, 0x418, v163
	v_add_u32_e32 v176, 0x820, v163
	v_add_u32_e32 v177, 0x828, v163
	v_add_u32_e32 v178, 0xc30, v163
	v_add_u32_e32 v179, 0xc38, v163
	v_add_u32_e32 v180, 0x1040, v163
	v_add_u32_e32 v181, 0x1048, v163
	v_add_u32_e32 v182, 0x1450, v163
	v_add_u32_e32 v183, 0x1458, v163
	v_add_u32_e32 v184, 0x1860, v163
	v_add_u32_e32 v185, 0x1868, v163
	v_add_u32_e32 v186, 0x1c70, v163
	v_add_u32_e32 v187, 0x1c78, v163
	v_add_u32_e32 v188, 0x2080, v163
	v_add_u32_e32 v189, 0x2088, v163
	v_add_u32_e32 v190, 0x2490, v163
	v_add_u32_e32 v191, 0x2498, v163
	v_add_u32_e32 v192, 0x28a0, v163
	v_add_u32_e32 v193, 0x28a8, v163
	v_add_u32_e32 v194, 0x2cb0, v163
	v_add_u32_e32 v195, 0x2cb8, v163
	v_add_u32_e32 v196, 0x30c0, v163
	v_add_u32_e32 v197, 0x30c8, v163
	v_add_u32_e32 v198, 0x34d0, v163
	v_add_u32_e32 v199, 0x34d8, v163
	v_add_u32_e32 v200, 0x38e0, v163
	v_add_u32_e32 v201, 0x38e8, v163
	v_add_u32_e32 v202, 0x3cf0, v163
	v_add_u32_e32 v203, 0x3cf8, v163
	s_waitcnt vmcnt(1)
	ds_write2_b32 v163, v16, v17 offset1:1
	ds_write2_b32 v163, v18, v19 offset0:2 offset1:3
	s_waitcnt vmcnt(0)
	ds_write2_b32 v174, v20, v21 offset1:1
	ds_write2_b32 v175, v22, v23 offset1:1
	ds_write2_b32 v176, v24, v25 offset1:1
	ds_write2_b32 v177, v26, v27 offset1:1
	ds_write2_b32 v178, v28, v29 offset1:1
	ds_write2_b32 v179, v30, v31 offset1:1
	ds_write2_b32 v180, v32, v33 offset1:1
	ds_write2_b32 v181, v34, v35 offset1:1
	ds_write2_b32 v182, v36, v37 offset1:1
	ds_write2_b32 v183, v38, v39 offset1:1
	ds_write2_b32 v184, v40, v41 offset1:1
	ds_write2_b32 v185, v42, v43 offset1:1
	ds_write2_b32 v186, v44, v45 offset1:1
	ds_write2_b32 v187, v46, v47 offset1:1
	ds_write2_b32 v188, v48, v49 offset1:1
	ds_write2_b32 v189, v50, v51 offset1:1
	ds_write2_b32 v190, v52, v53 offset1:1
	ds_write2_b32 v191, v54, v55 offset1:1
	ds_write2_b32 v192, v56, v57 offset1:1
	ds_write2_b32 v193, v58, v59 offset1:1
	ds_write2_b32 v194, v60, v61 offset1:1
	ds_write2_b32 v195, v62, v63 offset1:1
	ds_write2_b32 v196, v68, v69 offset1:1
	ds_write2_b32 v197, v70, v71 offset1:1
	ds_write2_b32 v198, v76, v77 offset1:1
	ds_write2_b32 v199, v78, v79 offset1:1
	ds_write2_b32 v200, v80, v81 offset1:1
	ds_write2_b32 v201, v82, v83 offset1:1
	ds_write2_b32 v202, v88, v89 offset1:1
	ds_write2_b32 v203, v90, v91 offset1:1
	s_waitcnt lgkmcnt(0)
	ds_read2_b32 v[2:3], v165 offset1:8
	ds_read2_b32 v[6:7], v165 offset0:65 offset1:73
	ds_read2_b32 v[208:209], v165 offset0:130 offset1:138
	ds_read2_b32 v[210:211], v165 offset0:195 offset1:203
	v_add_u32_e32 v173, 0x400, v165
	ds_read2_b32 v[212:213], v173 offset0:4 offset1:12
	ds_read2_b32 v[214:215], v173 offset0:69 offset1:77
	ds_read2_b32 v[216:217], v173 offset0:134 offset1:142
	ds_read2_b32 v[218:219], v173 offset0:199 offset1:207
	s_waitcnt lgkmcnt(7)
	v_mov_b32_e32 v204, v2
	s_waitcnt lgkmcnt(6)
	v_mov_b32_e32 v205, v6
	s_waitcnt lgkmcnt(5)
	v_mov_b32_e32 v206, v208
	s_waitcnt lgkmcnt(4)
	v_mov_b32_e32 v207, v210
	v_pk_mul_f32 v[204:205], v[12:13], v[204:205]
	v_pk_mul_f32 v[206:207], v[14:15], v[206:207]
	v_cvt_pk_bf16_f32 v204, v204, v205
	v_cvt_pk_bf16_f32 v205, v206, v207
	s_waitcnt lgkmcnt(3)
	v_mov_b32_e32 v206, v212
	s_waitcnt lgkmcnt(2)
	v_mov_b32_e32 v207, v214
	s_waitcnt lgkmcnt(1)
	v_mov_b32_e32 v220, v216
	s_waitcnt lgkmcnt(0)
	v_mov_b32_e32 v221, v218
	v_pk_mul_f32 v[206:207], v[8:9], v[206:207]
	v_pk_mul_f32 v[220:221], v[10:11], v[220:221]
	v_add_u32_e32 v1, s38, v164
	v_cvt_pk_bf16_f32 v206, v206, v207
	v_cvt_pk_bf16_f32 v207, v220, v221
	v_mad_i64_i32 v[220:221], s[28:29], s46, v1, 0
	s_ashr_i32 s17, s16, 31
	v_lshl_add_u64 v[220:221], v[220:221], 1, v[154:155]
	s_lshl_b64 s[28:29], s[16:17], 1
	v_lshl_add_u64 v[220:221], v[220:221], 0, s[28:29]
	v_mov_b32_e32 v159, v0
	v_mov_b32_e32 v6, v3
	v_lshl_add_u64 v[220:221], v[220:221], 0, v[158:159]
	v_pk_mul_f32 v[2:3], v[12:13], v[6:7]
	v_mov_b32_e32 v210, v209
	global_store_dwordx4 v[220:221], v[204:207], off sc1
	v_mov_b32_e32 v214, v213
	v_mov_b32_e32 v218, v217
	v_cvt_pk_bf16_f32 v204, v2, v3
	v_pk_mul_f32 v[2:3], v[14:15], v[210:211]
	v_add_u32_e32 v1, s38, v166
	v_cvt_pk_bf16_f32 v205, v2, v3
	v_pk_mul_f32 v[2:3], v[8:9], v[214:215]
	ds_read2_b32 v[6:7], v165 offset0:16 offset1:24
	v_cvt_pk_bf16_f32 v206, v2, v3
	v_pk_mul_f32 v[2:3], v[10:11], v[218:219]
	ds_read2_b32 v[208:209], v165 offset0:81 offset1:89
	v_cvt_pk_bf16_f32 v207, v2, v3
	v_mad_i64_i32 v[2:3], s[30:31], s46, v1, 0
	v_lshl_add_u64 v[2:3], v[2:3], 1, v[154:155]
	ds_read2_b32 v[210:211], v165 offset0:146 offset1:154
	ds_read2_b32 v[212:213], v165 offset0:211 offset1:219
	v_lshl_add_u64 v[2:3], v[2:3], 0, s[28:29]
	v_lshl_add_u64 v[2:3], v[2:3], 0, v[158:159]
	ds_read2_b32 v[214:215], v173 offset0:20 offset1:28
	ds_read2_b32 v[216:217], v173 offset0:85 offset1:93
	global_store_dwordx4 v[2:3], v[204:207], off sc1
	s_waitcnt lgkmcnt(5)
	v_mov_b32_e32 v2, v6
	s_waitcnt lgkmcnt(4)
	v_mov_b32_e32 v3, v208
	v_pk_mul_f32 v[2:3], v[12:13], v[2:3]
	ds_read2_b32 v[218:219], v173 offset0:150 offset1:158
	ds_read2_b32 v[220:221], v173 offset0:215 offset1:223
	v_cvt_pk_bf16_f32 v204, v2, v3
	s_waitcnt lgkmcnt(5)
	v_mov_b32_e32 v2, v210
	s_waitcnt lgkmcnt(4)
	v_mov_b32_e32 v3, v212
	v_pk_mul_f32 v[2:3], v[14:15], v[2:3]
	v_add_u32_e32 v1, s38, v167
	v_cvt_pk_bf16_f32 v205, v2, v3
	s_waitcnt lgkmcnt(3)
	v_mov_b32_e32 v2, v214
	s_waitcnt lgkmcnt(2)
	v_mov_b32_e32 v3, v216
	v_pk_mul_f32 v[2:3], v[8:9], v[2:3]
	v_mov_b32_e32 v208, v7
	v_cvt_pk_bf16_f32 v206, v2, v3
	s_waitcnt lgkmcnt(1)
	v_mov_b32_e32 v2, v218
	s_waitcnt lgkmcnt(0)
; #define GAS __attribute__((address_space(1)))
; #define LAS __attribute__((address_space(3)))
; #define LDS_WAIT() asm volatile("s_waitcnt lgkmcnt(0)" ::: "memory")
; DI unsigned pk2(float lo, float hi) { f32x2 v = {lo, hi}; bf16x2_t b = __builtin_convertvector(v, bf16x2_t); return __builtin_bit_cast(unsigned, b); }
; DI void tr_decode(const Frame& F, int git, TrItem& t) {
;     const int l = git / I_LAYER; int r = git - l * I_LAYER;
;     int s = 0;
;     if (r >= 3 * I_G + I_IN + I_OUT) { s = 1; r -= 3 * I_G + I_IN + I_OUT; }
;     if (r < 3 * I_G) {
;         const int kind = r / I_G; r -= kind * I_G; const int f = 2 * l + s;
;         if (kind < 2) {
;             const int up = kind;
;             t.W = F.in[s ? (up ? 21 : 20) : (up ? 3 : 2)] + (size_t)l * D * DFF; t.sc = F.in[s ? 19 : 1] + l * D;
;             const int kb = r / (DFF / 64), nb = r % (DFF / 64); t.k0 = 64 * kb; t.n0 = 64 * nb; t.N = DFF; t.Kd = D;
;             t.dst = (bf16*)(F.ws + WS_WGU + (size_t)f * SZ_WGU1); t.drow0 = 256 * (t.n0 >> 7) + (t.n0 & 127) + (up ? 128 : 0);
;         } else {
;             t.W = F.in[s ? 22 : 4] + (size_t)l * DFF * D; t.sc = nullptr;
;             const int kb = r / (D / 64), nb = r % (D / 64); t.k0 = 64 * kb; t.n0 = 64 * nb; t.N = D; t.Kd = DFF;
;             t.dst = (bf16*)(F.ws + WS_WD + (size_t)f * SZ_WD1); t.drow0 = t.n0;
;         }
;         return;
;     }
;     r -= 3 * I_G;
;     if (r < I_IN) {
;         t.W = F.in[6] + (size_t)l * D * DIN; t.sc = F.in[5] + l * D;
;         const int kb = r / 121, nb = r % 121; t.k0 = 64 * kb; t.n0 = 64 * nb; t.N = DIN; t.Kd = D;
;         t.dst = (bf16*)(F.ws + WS_WIN + (size_t)l * SZ_WIN1); t.drow0 = t.n0;
;         return;
;     }
;     r -= I_IN;
;     ...
;     for (int j = 0; j < 8; ++j) {
;         const int nn = (lane >> 3) + 8 * j; const LAS float* s = scr + (8 * c) * 65 + nn;
;         v4u o; o.x = pk2(s[0 * 65] * s0.x, s[1 * 65] * s0.y); o.y = pk2(s[2 * 65] * s0.z, s[3 * 65] * s0.w); o.z = pk2(s[4 * 65] * s1.x, s[5 * 65] * s1.y); o.w = pk2(s[6 * 65] * s1.z, s[7 * 65] * s1.w);
;         if (!(variant & 4)) *(GAS v4u*)(t.dst + (size_t)(t.drow0 + nn) * t.Kd + t.k0 + 8 * c) = o;
;         else asm volatile("" :: "v"(o));
;     }
;     LDS_WAIT(); asm volatile("" ::: "memory");
	v_mov_b32_e32 v3, v220
	v_pk_mul_f32 v[2:3], v[10:11], v[2:3]
	v_mov_b32_e32 v212, v211
	v_cvt_pk_bf16_f32 v207, v2, v3
	v_mad_i64_i32 v[2:3], s[30:31], s46, v1, 0
	v_lshl_add_u64 v[2:3], v[2:3], 1, v[154:155]
	v_lshl_add_u64 v[2:3], v[2:3], 0, s[28:29]
	v_lshl_add_u64 v[2:3], v[2:3], 0, v[158:159]
	global_store_dwordx4 v[2:3], v[204:207], off sc1
	v_pk_mul_f32 v[2:3], v[12:13], v[208:209]
	v_mov_b32_e32 v216, v215
	v_cvt_pk_bf16_f32 v204, v2, v3
	v_pk_mul_f32 v[2:3], v[14:15], v[212:213]
	v_mov_b32_e32 v220, v219
	v_cvt_pk_bf16_f32 v205, v2, v3
	v_pk_mul_f32 v[2:3], v[8:9], v[216:217]
	v_add_u32_e32 v1, s38, v168
	v_cvt_pk_bf16_f32 v206, v2, v3
	v_pk_mul_f32 v[2:3], v[10:11], v[220:221]
	ds_read2_b32 v[6:7], v165 offset0:32 offset1:40
	ds_read2_b32 v[208:209], v165 offset0:97 offset1:105
	v_cvt_pk_bf16_f32 v207, v2, v3
	v_mad_i64_i32 v[2:3], s[30:31], s46, v1, 0
	v_lshl_add_u64 v[2:3], v[2:3], 1, v[154:155]
	ds_read2_b32 v[210:211], v165 offset0:162 offset1:170
	ds_read2_b32 v[212:213], v165 offset0:227 offset1:235
	v_lshl_add_u64 v[2:3], v[2:3], 0, s[28:29]
	v_lshl_add_u64 v[2:3], v[2:3], 0, v[158:159]
	ds_read2_b32 v[214:215], v173 offset0:36 offset1:44
	ds_read2_b32 v[216:217], v173 offset0:101 offset1:109
	global_store_dwordx4 v[2:3], v[204:207], off sc1
	s_waitcnt lgkmcnt(5)
	v_mov_b32_e32 v2, v6
	s_waitcnt lgkmcnt(4)
	v_mov_b32_e32 v3, v208
	v_pk_mul_f32 v[2:3], v[12:13], v[2:3]
	ds_read2_b32 v[218:219], v173 offset0:166 offset1:174
	ds_read2_b32 v[220:221], v173 offset0:231 offset1:239
	v_cvt_pk_bf16_f32 v204, v2, v3
	s_waitcnt lgkmcnt(5)
	v_mov_b32_e32 v2, v210
	s_waitcnt lgkmcnt(4)
	v_mov_b32_e32 v3, v212
	v_pk_mul_f32 v[2:3], v[14:15], v[2:3]
	v_add_u32_e32 v1, s38, v169
	v_cvt_pk_bf16_f32 v205, v2, v3
	s_waitcnt lgkmcnt(3)
	v_mov_b32_e32 v2, v214
	s_waitcnt lgkmcnt(2)
	v_mov_b32_e32 v3, v216
	v_pk_mul_f32 v[2:3], v[8:9], v[2:3]
	v_mov_b32_e32 v208, v7
	v_cvt_pk_bf16_f32 v206, v2, v3
	s_waitcnt lgkmcnt(1)
	v_mov_b32_e32 v2, v218
	s_waitcnt lgkmcnt(0)
	v_mov_b32_e32 v3, v220
	v_pk_mul_f32 v[2:3], v[10:11], v[2:3]
	v_mov_b32_e32 v212, v211
	v_cvt_pk_bf16_f32 v207, v2, v3
	v_mad_i64_i32 v[2:3], s[30:31], s46, v1, 0
	v_lshl_add_u64 v[2:3], v[2:3], 1, v[154:155]
	v_lshl_add_u64 v[2:3], v[2:3], 0, s[28:29]
	v_lshl_add_u64 v[2:3], v[2:3], 0, v[158:159]
	global_store_dwordx4 v[2:3], v[204:207], off sc1
	v_pk_mul_f32 v[2:3], v[12:13], v[208:209]
	v_mov_b32_e32 v216, v215
	v_cvt_pk_bf16_f32 v204, v2, v3
	v_pk_mul_f32 v[2:3], v[14:15], v[212:213]
	v_mov_b32_e32 v220, v219
	v_cvt_pk_bf16_f32 v205, v2, v3
	v_pk_mul_f32 v[2:3], v[8:9], v[216:217]
	v_add_u32_e32 v1, s38, v170
	v_cvt_pk_bf16_f32 v206, v2, v3
	v_pk_mul_f32 v[2:3], v[10:11], v[220:221]
	ds_read2_b32 v[6:7], v165 offset0:48 offset1:56
	ds_read2_b32 v[208:209], v165 offset0:113 offset1:121
	v_cvt_pk_bf16_f32 v207, v2, v3
	v_mad_i64_i32 v[2:3], s[30:31], s46, v1, 0
	v_lshl_add_u64 v[2:3], v[2:3], 1, v[154:155]
	ds_read2_b32 v[210:211], v165 offset0:178 offset1:186
	ds_read2_b32 v[212:213], v165 offset0:243 offset1:251
	v_lshl_add_u64 v[2:3], v[2:3], 0, s[28:29]
	v_lshl_add_u64 v[2:3], v[2:3], 0, v[158:159]
	ds_read2_b32 v[214:215], v173 offset0:52 offset1:60
	ds_read2_b32 v[216:217], v173 offset0:117 offset1:125
	global_store_dwordx4 v[2:3], v[204:207], off sc1
	s_waitcnt lgkmcnt(5)
	v_mov_b32_e32 v2, v6
	s_waitcnt lgkmcnt(4)
	v_mov_b32_e32 v3, v208
	v_pk_mul_f32 v[2:3], v[12:13], v[2:3]
	ds_read2_b32 v[218:219], v173 offset0:182 offset1:190
	ds_read2_b32 v[220:221], v173 offset0:247 offset1:255
	v_cvt_pk_bf16_f32 v204, v2, v3
	s_waitcnt lgkmcnt(5)
	v_mov_b32_e32 v2, v210
	s_waitcnt lgkmcnt(4)
	v_mov_b32_e32 v3, v212
	v_pk_mul_f32 v[2:3], v[14:15], v[2:3]
	v_add_u32_e32 v1, s38, v171
	v_cvt_pk_bf16_f32 v205, v2, v3
	s_waitcnt lgkmcnt(3)
	v_mov_b32_e32 v2, v214
	s_waitcnt lgkmcnt(2)
	v_mov_b32_e32 v3, v216
	v_pk_mul_f32 v[2:3], v[8:9], v[2:3]
	v_mov_b32_e32 v208, v7
	v_cvt_pk_bf16_f32 v206, v2, v3
	s_waitcnt lgkmcnt(1)
	v_mov_b32_e32 v2, v218
	s_waitcnt lgkmcnt(0)
	v_mov_b32_e32 v3, v220
	v_pk_mul_f32 v[2:3], v[10:11], v[2:3]
	v_mov_b32_e32 v212, v211
	v_cvt_pk_bf16_f32 v207, v2, v3
	v_mad_i64_i32 v[2:3], s[30:31], s46, v1, 0
	v_lshl_add_u64 v[2:3], v[2:3], 1, v[154:155]
	v_lshl_add_u64 v[2:3], v[2:3], 0, s[28:29]
	v_lshl_add_u64 v[2:3], v[2:3], 0, v[158:159]
	global_store_dwordx4 v[2:3], v[204:207], off sc1
	v_pk_mul_f32 v[2:3], v[12:13], v[208:209]
	v_mov_b32_e32 v216, v215
	v_cvt_pk_bf16_f32 v204, v2, v3
	v_pk_mul_f32 v[2:3], v[14:15], v[212:213]
	v_mov_b32_e32 v220, v219
	v_cvt_pk_bf16_f32 v205, v2, v3
	v_pk_mul_f32 v[2:3], v[8:9], v[216:217]
	v_add_u32_e32 v1, s38, v172
	v_cvt_pk_bf16_f32 v206, v2, v3
	v_pk_mul_f32 v[2:3], v[10:11], v[220:221]
	s_add_i32 s58, s13, s52
	v_cvt_pk_bf16_f32 v207, v2, v3
	v_mad_i64_i32 v[2:3], s[30:31], s46, v1, 0
	v_lshl_add_u64 v[2:3], v[2:3], 1, v[154:155]
	v_lshl_add_u64 v[2:3], v[2:3], 0, s[28:29]
	v_lshl_add_u64 v[2:3], v[2:3], 0, v[158:159]
	global_store_dwordx4 v[2:3], v[204:207], off sc1
	s_waitcnt lgkmcnt(0)
	s_andn2_b64 vcc, exec, s[26:27]
	s_mov_b64 s[26:27], 0
	s_cbranch_vccnz .LBB0_52
	s_cmp_lt_i32 s58, s15
	s_cselect_b64 s[26:27], -1, 0
	s_cmp_ge_i32 s58, s15
	s_cbranch_scc1 .LBB0_51
	s_mul_hi_i32 s16, s58, 0xc0784b3
	s_lshr_b32 s17, s16, 31
	s_ashr_i32 s16, s16, 10
	s_add_i32 s30, s16, s17
	s_mul_i32 s16, s30, 0xffffaae0
	s_add_i32 s59, s58, s16
	s_cmpk_lt_i32 s59, 0x3420
	s_cselect_b64 s[34:35], -1, 0
	s_add_i32 s18, s59, 0xffffcbe0
	s_cmpk_gt_i32 s59, 0x341f
	s_cselect_b64 s[36:37], -1, 0
	s_and_b64 s[16:17], s[36:37], exec
	s_cselect_b32 s25, s18, s59
	s_cmpk_gt_i32 s25, 0x20ff
	s_mov_b64 s[42:43], -1
	s_cbranch_scc0 .LBB0_96
	s_ashr_i32 s31, s30, 31
	s_cmpk_gt_u32 s25, 0x301f
	s_mov_b64 s[40:41], -1
	s_cbranch_scc0 .LBB0_94
	s_load_dwordx2 s[16:17], s[8:9], 0x38
	s_lshl_b64 s[28:29], s[30:31], 24
	s_waitcnt lgkmcnt(0)
	s_add_u32 s28, s16, s28
	s_addc_u32 s29, s17, s29
	s_lshl_b32 s16, s25, 1
	s_lshl_b32 s17, s25, 6
	s_andn2_b32 s16, s16, 63
	s_and_b32 s60, s17, 0x7c0
	s_addk_i32 s16, 0x9fc0
	s_lshl_b64 s[40:41], s[30:31], 23
	s_add_u32 s44, s48, s40
	s_addc_u32 s45, s49, s41
	s_mov_b64 s[40:41], 0

; #define GAS __attribute__((address_space(1)))
; #define LAS __attribute__((address_space(3)))
; #define LDS_WAIT() asm volatile("s_waitcnt lgkmcnt(0)" ::: "memory")
; DI unsigned pk2(float lo, float hi) { f32x2 v = {lo, hi}; bf16x2_t b = __builtin_convertvector(v, bf16x2_t); return __builtin_bit_cast(unsigned, b); }
;     ...
;         LAS float* w = scr + (lane >> 4) * 65 + 4 * (lane & 15);
; #pragma unroll
;         for (int i = 0; i < 16; ++i) { w[(4 * i) * 65 + 0] = v[i].x; w[(4 * i) * 65 + 1] = v[i].y; w[(4 * i) * 65 + 2] = v[i].z; w[(4 * i) * 65 + 3] = v[i].w; }
;     }
;     LDS_WAIT(); asm volatile("" ::: "memory");
;     const int c = lane & 7;
;     const f32x4 s0 = sc[0], s1 = sc[1];
; #pragma unroll
;     for (int j = 0; j < 8; ++j) {
;         const int nn = (lane >> 3) + 8 * j; const LAS float* s = scr + (8 * c) * 65 + nn;
;         v4u o; o.x = pk2(s[0 * 65] * s0.x, s[1 * 65] * s0.y); o.y = pk2(s[2 * 65] * s0.z, s[3 * 65] * s0.w); o.z = pk2(s[4 * 65] * s1.x, s[5 * 65] * s1.y); o.w = pk2(s[6 * 65] * s1.z, s[7 * 65] * s1.w);
;         if (!(variant & 4)) *(GAS v4u*)(t.dst + (size_t)(t.drow0 + nn) * t.Kd + t.k0 + 8 * c) = o;
;         else asm volatile("" :: "v"(o));
;     }
;     LDS_WAIT(); asm volatile("" ::: "memory");
.LBB0_258:
	ds_write2_b32 v161, v80, v81 offset1:1
	ds_write2_b32 v161, v82, v83 offset0:2 offset1:3
	ds_write2_b32 v172, v84, v85 offset1:1
	ds_write2_b32 v173, v86, v87 offset1:1
	ds_write2_b32 v174, v88, v89 offset1:1
	ds_write2_b32 v175, v90, v91 offset1:1
	ds_write2_b32 v176, v92, v93 offset1:1
	ds_write2_b32 v177, v94, v95 offset1:1
	ds_write2_b32 v178, v104, v105 offset1:1
	ds_write2_b32 v179, v106, v107 offset1:1
	ds_write2_b32 v180, v108, v109 offset1:1
	ds_write2_b32 v181, v110, v111 offset1:1
	ds_write2_b32 v186, v112, v113 offset1:1
	ds_write2_b32 v187, v114, v115 offset1:1
	ds_write2_b32 v188, v116, v117 offset1:1
	ds_write2_b32 v189, v118, v119 offset1:1
	ds_write2_b32 v190, v120, v121 offset1:1
	ds_write2_b32 v191, v122, v123 offset1:1
	ds_write2_b32 v192, v124, v125 offset1:1
	ds_write2_b32 v193, v126, v127 offset1:1
	ds_write2_b32 v194, v128, v129 offset1:1
	ds_write2_b32 v195, v130, v131 offset1:1
	ds_write2_b32 v196, v132, v133 offset1:1
	ds_write2_b32 v197, v134, v135 offset1:1
	ds_write2_b32 v198, v136, v137 offset1:1
	ds_write2_b32 v199, v138, v139 offset1:1
	ds_write2_b32 v200, v144, v145 offset1:1
	ds_write2_b32 v201, v146, v147 offset1:1
	ds_write2_b32 v202, v140, v141 offset1:1
	ds_write2_b32 v203, v142, v143 offset1:1
	ds_write2_b32 v204, v148, v149 offset1:1
	ds_write2_b32 v205, v150, v151 offset1:1
	s_waitcnt lgkmcnt(0)
	ds_read2_b32 v[98:99], v163 offset1:8
	ds_read2_b32 v[102:103], v163 offset0:65 offset1:73
	ds_read2_b32 v[176:177], v163 offset0:130 offset1:138
	ds_read2_b32 v[178:179], v163 offset0:195 offset1:203
	ds_read2_b32 v[180:181], v171 offset0:4 offset1:12
	ds_read2_b32 v[186:187], v171 offset0:69 offset1:77
	ds_read2_b32 v[188:189], v171 offset0:134 offset1:142
	ds_read2_b32 v[190:191], v171 offset0:199 offset1:207
	s_waitcnt lgkmcnt(7)
	v_mov_b32_e32 v172, v98
	s_waitcnt lgkmcnt(6)
	v_mov_b32_e32 v173, v102
	s_waitcnt lgkmcnt(5)
	v_mov_b32_e32 v174, v176
	s_waitcnt lgkmcnt(4)
	v_mov_b32_e32 v175, v178
	v_pk_mul_f32 v[172:173], v[60:61], v[172:173]
	v_pk_mul_f32 v[174:175], v[62:63], v[174:175]
	v_cvt_pk_bf16_f32 v172, v172, v173
	v_cvt_pk_bf16_f32 v173, v174, v175
	s_waitcnt lgkmcnt(3)
	v_mov_b32_e32 v174, v180
	s_waitcnt lgkmcnt(2)
	v_mov_b32_e32 v175, v186
	s_waitcnt lgkmcnt(1)
	v_mov_b32_e32 v192, v188
	s_waitcnt lgkmcnt(0)
	v_mov_b32_e32 v193, v190
	v_pk_mul_f32 v[174:175], v[56:57], v[174:175]
	v_pk_mul_f32 v[192:193], v[58:59], v[192:193]
	v_add_u32_e32 v96, s69, v162
	v_cvt_pk_bf16_f32 v174, v174, v175
	v_cvt_pk_bf16_f32 v175, v192, v193
	v_mad_i64_i32 v[192:193], s[48:49], s70, v96, 0
	s_ashr_i32 s45, s44, 31
	v_lshl_add_u64 v[192:193], v[192:193], 1, v[158:159]
	s_lshl_b64 s[48:49], s[44:45], 1
	v_lshl_add_u64 v[192:193], v[192:193], 0, s[48:49]
	v_mov_b32_e32 v157, v97
	v_mov_b32_e32 v102, v99
	v_lshl_add_u64 v[192:193], v[192:193], 0, v[156:157]
	v_pk_mul_f32 v[98:99], v[60:61], v[102:103]
	v_mov_b32_e32 v178, v177
	global_store_dwordx4 v[192:193], v[172:175], off sc1
	v_mov_b32_e32 v186, v181
	v_mov_b32_e32 v190, v189
	v_cvt_pk_bf16_f32 v172, v98, v99
	v_pk_mul_f32 v[98:99], v[62:63], v[178:179]
	v_add_u32_e32 v96, s69, v164
	v_cvt_pk_bf16_f32 v173, v98, v99
	v_pk_mul_f32 v[98:99], v[56:57], v[186:187]
	ds_read2_b32 v[102:103], v163 offset0:16 offset1:24
	v_cvt_pk_bf16_f32 v174, v98, v99
	v_pk_mul_f32 v[98:99], v[58:59], v[190:191]
	ds_read2_b32 v[176:177], v163 offset0:81 offset1:89
	v_cvt_pk_bf16_f32 v175, v98, v99
	v_mad_i64_i32 v[98:99], s[50:51], s70, v96, 0
	v_lshl_add_u64 v[98:99], v[98:99], 1, v[158:159]
	ds_read2_b32 v[178:179], v163 offset0:146 offset1:154
	ds_read2_b32 v[180:181], v163 offset0:211 offset1:219
	v_lshl_add_u64 v[98:99], v[98:99], 0, s[48:49]
	v_lshl_add_u64 v[98:99], v[98:99], 0, v[156:157]
	ds_read2_b32 v[186:187], v171 offset0:20 offset1:28
	ds_read2_b32 v[188:189], v171 offset0:85 offset1:93
	global_store_dwordx4 v[98:99], v[172:175], off sc1
	s_waitcnt lgkmcnt(5)
	v_mov_b32_e32 v98, v102
	s_waitcnt lgkmcnt(4)
	v_mov_b32_e32 v99, v176
	v_pk_mul_f32 v[98:99], v[60:61], v[98:99]
	ds_read2_b32 v[190:191], v171 offset0:150 offset1:158
	ds_read2_b32 v[192:193], v171 offset0:215 offset1:223
	v_cvt_pk_bf16_f32 v172, v98, v99
	s_waitcnt lgkmcnt(5)
	v_mov_b32_e32 v98, v178
	s_waitcnt lgkmcnt(4)
	v_mov_b32_e32 v99, v180
	v_pk_mul_f32 v[98:99], v[62:63], v[98:99]
	v_add_u32_e32 v96, s69, v165
	v_cvt_pk_bf16_f32 v173, v98, v99
	s_waitcnt lgkmcnt(3)
	v_mov_b32_e32 v98, v186
	s_waitcnt lgkmcnt(2)
	v_mov_b32_e32 v99, v188
	v_pk_mul_f32 v[98:99], v[56:57], v[98:99]
	v_mov_b32_e32 v176, v103
	v_cvt_pk_bf16_f32 v174, v98, v99
	s_waitcnt lgkmcnt(1)
	v_mov_b32_e32 v98, v190
	s_waitcnt lgkmcnt(0)
; #define GAS __attribute__((address_space(1)))
; #define LAS __attribute__((address_space(3)))
; #define LDS_WAIT() asm volatile("s_waitcnt lgkmcnt(0)" ::: "memory")
; DI unsigned pk2(float lo, float hi) { f32x2 v = {lo, hi}; bf16x2_t b = __builtin_convertvector(v, bf16x2_t); return __builtin_bit_cast(unsigned, b); }
;     ...
;     for (int j = 0; j < 8; ++j) {
;         const int nn = (lane >> 3) + 8 * j; const LAS float* s = scr + (8 * c) * 65 + nn;
;         v4u o; o.x = pk2(s[0 * 65] * s0.x, s[1 * 65] * s0.y); o.y = pk2(s[2 * 65] * s0.z, s[3 * 65] * s0.w); o.z = pk2(s[4 * 65] * s1.x, s[5 * 65] * s1.y); o.w = pk2(s[6 * 65] * s1.z, s[7 * 65] * s1.w);
;         if (!(variant & 4)) *(GAS v4u*)(t.dst + (size_t)(t.drow0 + nn) * t.Kd + t.k0 + 8 * c) = o;
;         else asm volatile("" :: "v"(o));
;     }
;     LDS_WAIT(); asm volatile("" ::: "memory");
	v_mov_b32_e32 v99, v192
	v_pk_mul_f32 v[98:99], v[58:59], v[98:99]
	v_mov_b32_e32 v180, v179
	v_cvt_pk_bf16_f32 v175, v98, v99
	v_mad_i64_i32 v[98:99], s[50:51], s70, v96, 0
	v_lshl_add_u64 v[98:99], v[98:99], 1, v[158:159]
	v_lshl_add_u64 v[98:99], v[98:99], 0, s[48:49]
	v_lshl_add_u64 v[98:99], v[98:99], 0, v[156:157]
	global_store_dwordx4 v[98:99], v[172:175], off sc1
	v_pk_mul_f32 v[98:99], v[60:61], v[176:177]
	v_mov_b32_e32 v188, v187
	v_cvt_pk_bf16_f32 v172, v98, v99
	v_pk_mul_f32 v[98:99], v[62:63], v[180:181]
	v_mov_b32_e32 v192, v191
	v_cvt_pk_bf16_f32 v173, v98, v99
	v_pk_mul_f32 v[98:99], v[56:57], v[188:189]
	v_add_u32_e32 v96, s69, v166
	v_cvt_pk_bf16_f32 v174, v98, v99
	v_pk_mul_f32 v[98:99], v[58:59], v[192:193]
	ds_read2_b32 v[102:103], v163 offset0:32 offset1:40
	ds_read2_b32 v[176:177], v163 offset0:97 offset1:105
	v_cvt_pk_bf16_f32 v175, v98, v99
	v_mad_i64_i32 v[98:99], s[50:51], s70, v96, 0
	v_lshl_add_u64 v[98:99], v[98:99], 1, v[158:159]
	ds_read2_b32 v[178:179], v163 offset0:162 offset1:170
	ds_read2_b32 v[180:181], v163 offset0:227 offset1:235
	v_lshl_add_u64 v[98:99], v[98:99], 0, s[48:49]
	v_lshl_add_u64 v[98:99], v[98:99], 0, v[156:157]
	ds_read2_b32 v[186:187], v171 offset0:36 offset1:44
	ds_read2_b32 v[188:189], v171 offset0:101 offset1:109
	global_store_dwordx4 v[98:99], v[172:175], off sc1
	s_waitcnt lgkmcnt(5)
	v_mov_b32_e32 v98, v102
	s_waitcnt lgkmcnt(4)
	v_mov_b32_e32 v99, v176
	v_pk_mul_f32 v[98:99], v[60:61], v[98:99]
	ds_read2_b32 v[190:191], v171 offset0:166 offset1:174
	ds_read2_b32 v[192:193], v171 offset0:231 offset1:239
	v_cvt_pk_bf16_f32 v172, v98, v99
	s_waitcnt lgkmcnt(5)
	v_mov_b32_e32 v98, v178
	s_waitcnt lgkmcnt(4)
	v_mov_b32_e32 v99, v180
	v_pk_mul_f32 v[98:99], v[62:63], v[98:99]
	v_add_u32_e32 v96, s69, v167
	v_cvt_pk_bf16_f32 v173, v98, v99
	s_waitcnt lgkmcnt(3)
	v_mov_b32_e32 v98, v186
	s_waitcnt lgkmcnt(2)
	v_mov_b32_e32 v99, v188
	v_pk_mul_f32 v[98:99], v[56:57], v[98:99]
	v_mov_b32_e32 v176, v103
	v_cvt_pk_bf16_f32 v174, v98, v99
	s_waitcnt lgkmcnt(1)
	v_mov_b32_e32 v98, v190
	s_waitcnt lgkmcnt(0)
	v_mov_b32_e32 v99, v192
	v_pk_mul_f32 v[98:99], v[58:59], v[98:99]
	v_mov_b32_e32 v180, v179
	v_cvt_pk_bf16_f32 v175, v98, v99
	v_mad_i64_i32 v[98:99], s[50:51], s70, v96, 0
	v_lshl_add_u64 v[98:99], v[98:99], 1, v[158:159]
	v_lshl_add_u64 v[98:99], v[98:99], 0, s[48:49]
	v_lshl_add_u64 v[98:99], v[98:99], 0, v[156:157]
	global_store_dwordx4 v[98:99], v[172:175], off sc1
	v_pk_mul_f32 v[98:99], v[60:61], v[176:177]
	v_mov_b32_e32 v188, v187
	v_cvt_pk_bf16_f32 v172, v98, v99
	v_pk_mul_f32 v[98:99], v[62:63], v[180:181]
	v_mov_b32_e32 v192, v191
	v_cvt_pk_bf16_f32 v173, v98, v99
	v_pk_mul_f32 v[98:99], v[56:57], v[188:189]
	v_add_u32_e32 v96, s69, v168
	v_cvt_pk_bf16_f32 v174, v98, v99
	v_pk_mul_f32 v[98:99], v[58:59], v[192:193]
	ds_read2_b32 v[102:103], v163 offset0:48 offset1:56
	ds_read2_b32 v[176:177], v163 offset0:113 offset1:121
	v_cvt_pk_bf16_f32 v175, v98, v99
	v_mad_i64_i32 v[98:99], s[50:51], s70, v96, 0
	v_lshl_add_u64 v[98:99], v[98:99], 1, v[158:159]
	ds_read2_b32 v[178:179], v163 offset0:178 offset1:186
	ds_read2_b32 v[180:181], v163 offset0:243 offset1:251
	v_lshl_add_u64 v[98:99], v[98:99], 0, s[48:49]
	v_lshl_add_u64 v[98:99], v[98:99], 0, v[156:157]
	ds_read2_b32 v[186:187], v171 offset0:52 offset1:60
	ds_read2_b32 v[188:189], v171 offset0:117 offset1:125
	global_store_dwordx4 v[98:99], v[172:175], off sc1
	s_waitcnt lgkmcnt(5)
	v_mov_b32_e32 v98, v102
	s_waitcnt lgkmcnt(4)
	v_mov_b32_e32 v99, v176
	v_pk_mul_f32 v[98:99], v[60:61], v[98:99]
	ds_read2_b32 v[190:191], v171 offset0:182 offset1:190
	ds_read2_b32 v[192:193], v171 offset0:247 offset1:255
	v_cvt_pk_bf16_f32 v172, v98, v99
	s_waitcnt lgkmcnt(5)
	v_mov_b32_e32 v98, v178
	s_waitcnt lgkmcnt(4)
	v_mov_b32_e32 v99, v180
	v_pk_mul_f32 v[98:99], v[62:63], v[98:99]
	v_add_u32_e32 v96, s69, v169
	v_cvt_pk_bf16_f32 v173, v98, v99
	s_waitcnt lgkmcnt(3)
	v_mov_b32_e32 v98, v186
	s_waitcnt lgkmcnt(2)
	v_mov_b32_e32 v99, v188
	v_pk_mul_f32 v[98:99], v[56:57], v[98:99]
	v_mov_b32_e32 v176, v103
	v_cvt_pk_bf16_f32 v174, v98, v99
	s_waitcnt lgkmcnt(1)
	v_mov_b32_e32 v98, v190
	s_waitcnt lgkmcnt(0)
	v_mov_b32_e32 v99, v192
	v_pk_mul_f32 v[98:99], v[58:59], v[98:99]
	v_mov_b32_e32 v180, v179
	v_cvt_pk_bf16_f32 v175, v98, v99
	v_mad_i64_i32 v[98:99], s[50:51], s70, v96, 0
	v_lshl_add_u64 v[98:99], v[98:99], 1, v[158:159]
	v_lshl_add_u64 v[98:99], v[98:99], 0, s[48:49]
	v_lshl_add_u64 v[98:99], v[98:99], 0, v[156:157]
	global_store_dwordx4 v[98:99], v[172:175], off sc1
	v_pk_mul_f32 v[98:99], v[60:61], v[176:177]
	v_mov_b32_e32 v188, v187
	v_cvt_pk_bf16_f32 v172, v98, v99
	v_pk_mul_f32 v[98:99], v[62:63], v[180:181]
	v_mov_b32_e32 v192, v191
	v_cvt_pk_bf16_f32 v173, v98, v99
	v_pk_mul_f32 v[98:99], v[56:57], v[188:189]
	v_add_u32_e32 v96, s69, v170
	v_cvt_pk_bf16_f32 v174, v98, v99
	v_pk_mul_f32 v[98:99], v[58:59], v[192:193]
	s_nop 0
	v_cvt_pk_bf16_f32 v175, v98, v99
	v_mad_i64_i32 v[98:99], s[50:51], s70, v96, 0
	v_lshl_add_u64 v[98:99], v[98:99], 1, v[158:159]
	v_lshl_add_u64 v[98:99], v[98:99], 0, s[48:49]
	v_lshl_add_u64 v[98:99], v[98:99], 0, v[156:157]
	global_store_dwordx4 v[98:99], v[172:175], off sc1
	s_waitcnt lgkmcnt(0)

; #define GAS __attribute__((address_space(1)))
; #define LAS __attribute__((address_space(3)))
; #define LDS_WAIT() asm volatile("s_waitcnt lgkmcnt(0)" ::: "memory")
; DI unsigned pk2(float lo, float hi) { f32x2 v = {lo, hi}; bf16x2_t b = __builtin_convertvector(v, bf16x2_t); return __builtin_bit_cast(unsigned, b); }
;     ...
;         LAS float* w = scr + (lane >> 4) * 65 + 4 * (lane & 15);
; #pragma unroll
;         for (int i = 0; i < 16; ++i) { w[(4 * i) * 65 + 0] = v[i].x; w[(4 * i) * 65 + 1] = v[i].y; w[(4 * i) * 65 + 2] = v[i].z; w[(4 * i) * 65 + 3] = v[i].w; }
;     }
;     LDS_WAIT(); asm volatile("" ::: "memory");
;     const int c = lane & 7;
;     const f32x4 s0 = sc[0], s1 = sc[1];
; #pragma unroll
;     for (int j = 0; j < 8; ++j) {
;         const int nn = (lane >> 3) + 8 * j; const LAS float* s = scr + (8 * c) * 65 + nn;
;         v4u o; o.x = pk2(s[0 * 65] * s0.x, s[1 * 65] * s0.y); o.y = pk2(s[2 * 65] * s0.z, s[3 * 65] * s0.w); o.z = pk2(s[4 * 65] * s1.x, s[5 * 65] * s1.y); o.w = pk2(s[6 * 65] * s1.z, s[7 * 65] * s1.w);
;         if (!(variant & 4)) *(GAS v4u*)(t.dst + (size_t)(t.drow0 + nn) * t.Kd + t.k0 + 8 * c) = o;
;         else asm volatile("" :: "v"(o));
;     }
;     LDS_WAIT(); asm volatile("" ::: "memory");
.LBB0_296:
	v_add_u32_e32 v172, 0x410, v161
	v_add_u32_e32 v173, 0x418, v161
	v_add_u32_e32 v174, 0x820, v161
	v_add_u32_e32 v175, 0x828, v161
	v_add_u32_e32 v176, 0xc30, v161
	v_add_u32_e32 v177, 0xc38, v161
	v_add_u32_e32 v178, 0x1040, v161
	v_add_u32_e32 v179, 0x1048, v161
	v_add_u32_e32 v180, 0x1450, v161
	v_add_u32_e32 v181, 0x1458, v161
	v_add_u32_e32 v186, 0x1860, v161
	v_add_u32_e32 v187, 0x1868, v161
	v_add_u32_e32 v188, 0x1c70, v161
	v_add_u32_e32 v189, 0x1c78, v161
	v_add_u32_e32 v190, 0x2080, v161
	v_add_u32_e32 v191, 0x2088, v161
	v_add_u32_e32 v192, 0x2490, v161
	v_add_u32_e32 v193, 0x2498, v161
	v_add_u32_e32 v194, 0x28a0, v161
	v_add_u32_e32 v195, 0x28a8, v161
	v_add_u32_e32 v196, 0x2cb0, v161
	v_add_u32_e32 v197, 0x2cb8, v161
	v_add_u32_e32 v198, 0x30c0, v161
	v_add_u32_e32 v199, 0x30c8, v161
	v_add_u32_e32 v200, 0x34d0, v161
	v_add_u32_e32 v201, 0x34d8, v161
	v_add_u32_e32 v202, 0x38e0, v161
	v_add_u32_e32 v203, 0x38e8, v161
	v_add_u32_e32 v204, 0x3cf0, v161
	v_add_u32_e32 v205, 0x3cf8, v161
	s_waitcnt vmcnt(0)
	ds_write2_b32 v161, v8, v9 offset1:1
	ds_write2_b32 v161, v10, v11 offset0:2 offset1:3
	ds_write2_b32 v172, v12, v13 offset1:1
	ds_write2_b32 v173, v14, v15 offset1:1
	ds_write2_b32 v174, v16, v17 offset1:1
	ds_write2_b32 v175, v18, v19 offset1:1
	ds_write2_b32 v176, v20, v21 offset1:1
	ds_write2_b32 v177, v22, v23 offset1:1
	ds_write2_b32 v178, v24, v25 offset1:1
	ds_write2_b32 v179, v26, v27 offset1:1
	ds_write2_b32 v180, v28, v29 offset1:1
	ds_write2_b32 v181, v30, v31 offset1:1
	ds_write2_b32 v186, v32, v33 offset1:1
	ds_write2_b32 v187, v34, v35 offset1:1
	ds_write2_b32 v188, v36, v37 offset1:1
	ds_write2_b32 v189, v38, v39 offset1:1
	ds_write2_b32 v190, v40, v41 offset1:1
	ds_write2_b32 v191, v42, v43 offset1:1
	ds_write2_b32 v192, v44, v45 offset1:1
	ds_write2_b32 v193, v46, v47 offset1:1
	ds_write2_b32 v194, v48, v49 offset1:1
	ds_write2_b32 v195, v50, v51 offset1:1
	ds_write2_b32 v196, v52, v53 offset1:1
	ds_write2_b32 v197, v54, v55 offset1:1
	ds_write2_b32 v198, v64, v65 offset1:1
	ds_write2_b32 v199, v66, v67 offset1:1
	ds_write2_b32 v200, v68, v69 offset1:1
	ds_write2_b32 v201, v70, v71 offset1:1
	ds_write2_b32 v202, v72, v73 offset1:1
	ds_write2_b32 v203, v74, v75 offset1:1
	ds_write2_b32 v204, v76, v77 offset1:1
	ds_write2_b32 v205, v78, v79 offset1:1
	s_waitcnt lgkmcnt(0)
	ds_read2_b32 v[98:99], v163 offset1:8
	ds_read2_b32 v[102:103], v163 offset0:65 offset1:73
	ds_read2_b32 v[210:211], v163 offset0:130 offset1:138
	ds_read2_b32 v[212:213], v163 offset0:195 offset1:203
	v_add_u32_e32 v171, 0x400, v163
	ds_read2_b32 v[214:215], v171 offset0:4 offset1:12
	ds_read2_b32 v[216:217], v171 offset0:69 offset1:77
	ds_read2_b32 v[218:219], v171 offset0:134 offset1:142
	ds_read2_b32 v[220:221], v171 offset0:199 offset1:207
	s_waitcnt lgkmcnt(0)
	v_mov_b32_e32 v206, v98
	v_mov_b32_e32 v207, v102
	v_mov_b32_e32 v208, v210
	v_mov_b32_e32 v209, v212
	v_pk_mul_f32 v[206:207], v[4:5], v[206:207]
	v_pk_mul_f32 v[208:209], v[6:7], v[208:209]
	v_cvt_pk_bf16_f32 v206, v206, v207
	v_cvt_pk_bf16_f32 v207, v208, v209
	v_mov_b32_e32 v208, v214
	v_mov_b32_e32 v209, v216
	v_mov_b32_e32 v222, v218
	v_mov_b32_e32 v223, v220
	v_pk_mul_f32 v[208:209], v[0:1], v[208:209]
	v_pk_mul_f32 v[222:223], v[2:3], v[222:223]
	v_add_u32_e32 v96, s38, v162
	v_cvt_pk_bf16_f32 v208, v208, v209
	v_cvt_pk_bf16_f32 v209, v222, v223
	v_mad_i64_i32 v[222:223], s[48:49], s39, v96, 0
	s_ashr_i32 s31, s30, 31
	v_lshl_add_u64 v[222:223], v[222:223], 1, v[152:153]
	s_lshl_b64 s[48:49], s[30:31], 1
	v_lshl_add_u64 v[222:223], v[222:223], 0, s[48:49]
	v_mov_b32_e32 v157, v97
	v_mov_b32_e32 v102, v99
	v_lshl_add_u64 v[222:223], v[222:223], 0, v[156:157]
	v_pk_mul_f32 v[98:99], v[4:5], v[102:103]
	v_mov_b32_e32 v212, v211
	global_store_dwordx4 v[222:223], v[206:209], off sc1
	v_mov_b32_e32 v216, v215
	v_mov_b32_e32 v220, v219
	v_cvt_pk_bf16_f32 v206, v98, v99
	v_pk_mul_f32 v[98:99], v[6:7], v[212:213]
	v_add_u32_e32 v96, s38, v164
	v_cvt_pk_bf16_f32 v207, v98, v99
	v_pk_mul_f32 v[98:99], v[0:1], v[216:217]
	ds_read2_b32 v[102:103], v163 offset0:16 offset1:24
	v_cvt_pk_bf16_f32 v208, v98, v99
	v_pk_mul_f32 v[98:99], v[2:3], v[220:221]
	ds_read2_b32 v[210:211], v163 offset0:81 offset1:89
	v_cvt_pk_bf16_f32 v209, v98, v99
	v_mad_i64_i32 v[98:99], s[50:51], s39, v96, 0
	v_lshl_add_u64 v[98:99], v[98:99], 1, v[152:153]
	ds_read2_b32 v[212:213], v163 offset0:146 offset1:154
	ds_read2_b32 v[214:215], v163 offset0:211 offset1:219
	v_lshl_add_u64 v[98:99], v[98:99], 0, s[48:49]
	v_lshl_add_u64 v[98:99], v[98:99], 0, v[156:157]
	ds_read2_b32 v[216:217], v171 offset0:20 offset1:28
	ds_read2_b32 v[218:219], v171 offset0:85 offset1:93
	global_store_dwordx4 v[98:99], v[206:209], off sc1
	s_waitcnt lgkmcnt(5)
	v_mov_b32_e32 v98, v102
	s_waitcnt lgkmcnt(4)
	v_mov_b32_e32 v99, v210
	v_pk_mul_f32 v[98:99], v[4:5], v[98:99]
	ds_read2_b32 v[220:221], v171 offset0:150 offset1:158
	ds_read2_b32 v[222:223], v171 offset0:215 offset1:223
	v_cvt_pk_bf16_f32 v206, v98, v99
	s_waitcnt lgkmcnt(5)
	v_mov_b32_e32 v98, v212
	s_waitcnt lgkmcnt(4)
	v_mov_b32_e32 v99, v214
	v_pk_mul_f32 v[98:99], v[6:7], v[98:99]
	v_add_u32_e32 v96, s38, v165
	v_cvt_pk_bf16_f32 v207, v98, v99
	s_waitcnt lgkmcnt(3)
	v_mov_b32_e32 v98, v216
	s_waitcnt lgkmcnt(2)
	v_mov_b32_e32 v99, v218
	v_pk_mul_f32 v[98:99], v[0:1], v[98:99]
	v_mov_b32_e32 v210, v103
	v_cvt_pk_bf16_f32 v208, v98, v99
	s_waitcnt lgkmcnt(1)
	v_mov_b32_e32 v98, v220
	s_waitcnt lgkmcnt(0)
; #define GAS __attribute__((address_space(1)))
; #define LAS __attribute__((address_space(3)))
; #define LDS_WAIT() asm volatile("s_waitcnt lgkmcnt(0)" ::: "memory")
; DI unsigned pk2(float lo, float hi) { f32x2 v = {lo, hi}; bf16x2_t b = __builtin_convertvector(v, bf16x2_t); return __builtin_bit_cast(unsigned, b); }
; DI void tr_decode(const Frame& F, int git, TrItem& t) {
;     const int l = git / I_LAYER; int r = git - l * I_LAYER;
;     int s = 0;
;     if (r >= 3 * I_G + I_IN + I_OUT) { s = 1; r -= 3 * I_G + I_IN + I_OUT; }
;     if (r < 3 * I_G) {
;         const int kind = r / I_G; r -= kind * I_G; const int f = 2 * l + s;
;         if (kind < 2) {
;             const int up = kind;
;             t.W = F.in[s ? (up ? 21 : 20) : (up ? 3 : 2)] + (size_t)l * D * DFF; t.sc = F.in[s ? 19 : 1] + l * D;
;             const int kb = r / (DFF / 64), nb = r % (DFF / 64); t.k0 = 64 * kb; t.n0 = 64 * nb; t.N = DFF; t.Kd = D;
;             t.dst = (bf16*)(F.ws + WS_WGU + (size_t)f * SZ_WGU1); t.drow0 = 256 * (t.n0 >> 7) + (t.n0 & 127) + (up ? 128 : 0);
;         } else {
;             t.W = F.in[s ? 22 : 4] + (size_t)l * DFF * D; t.sc = nullptr;
;             const int kb = r / (D / 64), nb = r % (D / 64); t.k0 = 64 * kb; t.n0 = 64 * nb; t.N = D; t.Kd = DFF;
;             t.dst = (bf16*)(F.ws + WS_WD + (size_t)f * SZ_WD1); t.drow0 = t.n0;
;         }
;         return;
;     }
;     r -= 3 * I_G;
;     if (r < I_IN) {
;         t.W = F.in[6] + (size_t)l * D * DIN; t.sc = F.in[5] + l * D;
;         const int kb = r / 121, nb = r % 121; t.k0 = 64 * kb; t.n0 = 64 * nb; t.N = DIN; t.Kd = D;
;         t.dst = (bf16*)(F.ws + WS_WIN + (size_t)l * SZ_WIN1); t.drow0 = t.n0;
;         return;
;     }
;     r -= I_IN;
;     ...
;     for (int j = 0; j < 8; ++j) {
;         const int nn = (lane >> 3) + 8 * j; const LAS float* s = scr + (8 * c) * 65 + nn;
;         v4u o; o.x = pk2(s[0 * 65] * s0.x, s[1 * 65] * s0.y); o.y = pk2(s[2 * 65] * s0.z, s[3 * 65] * s0.w); o.z = pk2(s[4 * 65] * s1.x, s[5 * 65] * s1.y); o.w = pk2(s[6 * 65] * s1.z, s[7 * 65] * s1.w);
;         if (!(variant & 4)) *(GAS v4u*)(t.dst + (size_t)(t.drow0 + nn) * t.Kd + t.k0 + 8 * c) = o;
;         else asm volatile("" :: "v"(o));
;     }
;     LDS_WAIT(); asm volatile("" ::: "memory");
	v_mov_b32_e32 v99, v222
	v_pk_mul_f32 v[98:99], v[2:3], v[98:99]
	v_mov_b32_e32 v214, v213
	v_cvt_pk_bf16_f32 v209, v98, v99
	v_mad_i64_i32 v[98:99], s[50:51], s39, v96, 0
	v_lshl_add_u64 v[98:99], v[98:99], 1, v[152:153]
	v_lshl_add_u64 v[98:99], v[98:99], 0, s[48:49]
	v_lshl_add_u64 v[98:99], v[98:99], 0, v[156:157]
	global_store_dwordx4 v[98:99], v[206:209], off sc1
	v_pk_mul_f32 v[98:99], v[4:5], v[210:211]
	v_mov_b32_e32 v218, v217
	v_cvt_pk_bf16_f32 v206, v98, v99
	v_pk_mul_f32 v[98:99], v[6:7], v[214:215]
	v_mov_b32_e32 v222, v221
	v_cvt_pk_bf16_f32 v207, v98, v99
	v_pk_mul_f32 v[98:99], v[0:1], v[218:219]
	v_add_u32_e32 v96, s38, v166
	v_cvt_pk_bf16_f32 v208, v98, v99
	v_pk_mul_f32 v[98:99], v[2:3], v[222:223]
	ds_read2_b32 v[102:103], v163 offset0:32 offset1:40
	ds_read2_b32 v[210:211], v163 offset0:97 offset1:105
	v_cvt_pk_bf16_f32 v209, v98, v99
	v_mad_i64_i32 v[98:99], s[50:51], s39, v96, 0
	v_lshl_add_u64 v[98:99], v[98:99], 1, v[152:153]
	ds_read2_b32 v[212:213], v163 offset0:162 offset1:170
	ds_read2_b32 v[214:215], v163 offset0:227 offset1:235
	v_lshl_add_u64 v[98:99], v[98:99], 0, s[48:49]
	v_lshl_add_u64 v[98:99], v[98:99], 0, v[156:157]
	ds_read2_b32 v[216:217], v171 offset0:36 offset1:44
	ds_read2_b32 v[218:219], v171 offset0:101 offset1:109
	global_store_dwordx4 v[98:99], v[206:209], off sc1
	s_waitcnt lgkmcnt(5)
	v_mov_b32_e32 v98, v102
	s_waitcnt lgkmcnt(4)
	v_mov_b32_e32 v99, v210
	v_pk_mul_f32 v[98:99], v[4:5], v[98:99]
	ds_read2_b32 v[220:221], v171 offset0:166 offset1:174
	ds_read2_b32 v[222:223], v171 offset0:231 offset1:239
	v_cvt_pk_bf16_f32 v206, v98, v99
	s_waitcnt lgkmcnt(5)
	v_mov_b32_e32 v98, v212
	s_waitcnt lgkmcnt(4)
	v_mov_b32_e32 v99, v214
	v_pk_mul_f32 v[98:99], v[6:7], v[98:99]
	v_add_u32_e32 v96, s38, v167
	v_cvt_pk_bf16_f32 v207, v98, v99
	s_waitcnt lgkmcnt(3)
	v_mov_b32_e32 v98, v216
	s_waitcnt lgkmcnt(2)
	v_mov_b32_e32 v99, v218
	v_pk_mul_f32 v[98:99], v[0:1], v[98:99]
	v_mov_b32_e32 v210, v103
	v_cvt_pk_bf16_f32 v208, v98, v99
	s_waitcnt lgkmcnt(1)
	v_mov_b32_e32 v98, v220
	s_waitcnt lgkmcnt(0)
	v_mov_b32_e32 v99, v222
	v_pk_mul_f32 v[98:99], v[2:3], v[98:99]
	v_mov_b32_e32 v214, v213
	v_cvt_pk_bf16_f32 v209, v98, v99
	v_mad_i64_i32 v[98:99], s[50:51], s39, v96, 0
	v_lshl_add_u64 v[98:99], v[98:99], 1, v[152:153]
	v_lshl_add_u64 v[98:99], v[98:99], 0, s[48:49]
	v_lshl_add_u64 v[98:99], v[98:99], 0, v[156:157]
	global_store_dwordx4 v[98:99], v[206:209], off sc1
	v_pk_mul_f32 v[98:99], v[4:5], v[210:211]
	v_mov_b32_e32 v218, v217
	v_cvt_pk_bf16_f32 v206, v98, v99
	v_pk_mul_f32 v[98:99], v[6:7], v[214:215]
	v_mov_b32_e32 v222, v221
	v_cvt_pk_bf16_f32 v207, v98, v99
	v_pk_mul_f32 v[98:99], v[0:1], v[218:219]
	v_add_u32_e32 v96, s38, v168
	v_cvt_pk_bf16_f32 v208, v98, v99
	v_pk_mul_f32 v[98:99], v[2:3], v[222:223]
	ds_read2_b32 v[102:103], v163 offset0:48 offset1:56
	ds_read2_b32 v[210:211], v163 offset0:113 offset1:121
	v_cvt_pk_bf16_f32 v209, v98, v99
	v_mad_i64_i32 v[98:99], s[50:51], s39, v96, 0
	v_lshl_add_u64 v[98:99], v[98:99], 1, v[152:153]
	ds_read2_b32 v[212:213], v163 offset0:178 offset1:186
	ds_read2_b32 v[214:215], v163 offset0:243 offset1:251
	v_lshl_add_u64 v[98:99], v[98:99], 0, s[48:49]
	v_lshl_add_u64 v[98:99], v[98:99], 0, v[156:157]
	ds_read2_b32 v[216:217], v171 offset0:52 offset1:60
	ds_read2_b32 v[218:219], v171 offset0:117 offset1:125
	global_store_dwordx4 v[98:99], v[206:209], off sc1
	s_waitcnt lgkmcnt(5)
	v_mov_b32_e32 v98, v102
	s_waitcnt lgkmcnt(4)
	v_mov_b32_e32 v99, v210
	v_pk_mul_f32 v[98:99], v[4:5], v[98:99]
	ds_read2_b32 v[220:221], v171 offset0:182 offset1:190
	ds_read2_b32 v[222:223], v171 offset0:247 offset1:255
	v_cvt_pk_bf16_f32 v206, v98, v99
	s_waitcnt lgkmcnt(5)
	v_mov_b32_e32 v98, v212
	s_waitcnt lgkmcnt(4)
	v_mov_b32_e32 v99, v214
	v_pk_mul_f32 v[98:99], v[6:7], v[98:99]
	v_add_u32_e32 v96, s38, v169
	v_cvt_pk_bf16_f32 v207, v98, v99
	s_waitcnt lgkmcnt(3)
	v_mov_b32_e32 v98, v216
	s_waitcnt lgkmcnt(2)
	v_mov_b32_e32 v99, v218
	v_pk_mul_f32 v[98:99], v[0:1], v[98:99]
	v_mov_b32_e32 v210, v103
	v_cvt_pk_bf16_f32 v208, v98, v99
	s_waitcnt lgkmcnt(1)
	v_mov_b32_e32 v98, v220
	s_waitcnt lgkmcnt(0)
	v_mov_b32_e32 v99, v222
	v_pk_mul_f32 v[98:99], v[2:3], v[98:99]
	v_mov_b32_e32 v214, v213
	v_cvt_pk_bf16_f32 v209, v98, v99
	v_mad_i64_i32 v[98:99], s[50:51], s39, v96, 0
	v_lshl_add_u64 v[98:99], v[98:99], 1, v[152:153]
	v_lshl_add_u64 v[98:99], v[98:99], 0, s[48:49]
	v_lshl_add_u64 v[98:99], v[98:99], 0, v[156:157]
	global_store_dwordx4 v[98:99], v[206:209], off sc1
	v_pk_mul_f32 v[98:99], v[4:5], v[210:211]
	v_mov_b32_e32 v218, v217
	v_cvt_pk_bf16_f32 v206, v98, v99
	v_pk_mul_f32 v[98:99], v[6:7], v[214:215]
	v_mov_b32_e32 v222, v221
	v_cvt_pk_bf16_f32 v207, v98, v99
	v_pk_mul_f32 v[98:99], v[0:1], v[218:219]
	v_add_u32_e32 v96, s38, v170
	v_cvt_pk_bf16_f32 v208, v98, v99
	v_pk_mul_f32 v[98:99], v[2:3], v[222:223]
	s_add_i32 s71, s68, 0xfffff501
	v_cvt_pk_bf16_f32 v209, v98, v99
	v_mad_i64_i32 v[98:99], s[50:51], s39, v96, 0
	v_lshl_add_u64 v[98:99], v[98:99], 1, v[152:153]
	v_lshl_add_u64 v[98:99], v[98:99], 0, s[48:49]
	v_lshl_add_u64 v[98:99], v[98:99], 0, v[156:157]
	global_store_dwordx4 v[98:99], v[206:209], off sc1
	s_waitcnt lgkmcnt(0)
	s_andn2_b64 vcc, exec, s[46:47]
	s_mov_b64 s[46:47], 0
	s_cbranch_vccnz .LBB0_259
	s_cmp_lt_i32 s71, s36
	s_cselect_b64 s[46:47], -1, 0
	s_cmp_ge_i32 s71, s36
	s_cbranch_scc1 .LBB0_258
	s_mul_hi_i32 s2, s71, 0xc0784b3
	s_lshr_b32 s30, s2, 31
	s_ashr_i32 s2, s2, 10
	s_add_i32 s50, s2, s30
	s_mul_i32 s2, s50, 0xffffaae0
	s_add_i32 s73, s68, s2
	s_add_i32 s72, s73, 0xfffff501
	s_cmpk_lt_i32 s72, 0x3420
	s_cselect_b64 s[54:55], -1, 0
	s_add_i32 s2, s73, 0xffffc0e1
	s_cmpk_gt_i32 s72, 0x341f
	s_cselect_b64 s[56:57], -1, 0
	s_and_b64 s[30:31], s[56:57], exec
	s_cselect_b32 s45, s2, s72
	s_cmpk_gt_i32 s45, 0x20ff
	s_mov_b64 s[58:59], -1
	s_cbranch_scc0 .LBB0_303
	s_ashr_i32 s51, s50, 31
	s_cmpk_gt_u32 s45, 0x301f
	s_mov_b64 s[52:53], -1
	s_cbranch_scc0 .LBB0_301
	s_load_dwordx2 s[30:31], s[0:1], 0x38
	s_lshl_b64 s[38:39], s[50:51], 24
	s_mov_b64 s[52:53], 0
	s_waitcnt lgkmcnt(0)
	s_add_u32 s48, s30, s38
	s_addc_u32 s49, s31, s39
	s_lshl_b32 s2, s45, 1
	s_lshl_b32 s30, s45, 6
	s_andn2_b32 s2, s2, 63
	s_and_b32 s75, s30, 0x7c0
	s_add_i32 s30, s2, 0xffff9fc0
	s_lshl_b64 s[38:39], s[50:51], 23
	s_add_u32 s60, s64, s38
	s_addc_u32 s61, s65, s39

; #define GAS __attribute__((address_space(1)))
; #define LAS __attribute__((address_space(3)))
; #define LDS_WAIT() asm volatile("s_waitcnt lgkmcnt(0)" ::: "memory")
; DI unsigned pk2(float lo, float hi) { f32x2 v = {lo, hi}; bf16x2_t b = __builtin_convertvector(v, bf16x2_t); return __builtin_bit_cast(unsigned, b); }
;     ...
;         LAS float* w = scr + (lane >> 4) * 65 + 4 * (lane & 15);
; #pragma unroll
;         for (int i = 0; i < 16; ++i) { w[(4 * i) * 65 + 0] = v[i].x; w[(4 * i) * 65 + 1] = v[i].y; w[(4 * i) * 65 + 2] = v[i].z; w[(4 * i) * 65 + 3] = v[i].w; }
;     }
;     LDS_WAIT(); asm volatile("" ::: "memory");
;     const int c = lane & 7;
;     const f32x4 s0 = sc[0], s1 = sc[1];
; #pragma unroll
;     for (int j = 0; j < 8; ++j) {
;         const int nn = (lane >> 3) + 8 * j; const LAS float* s = scr + (8 * c) * 65 + nn;
;         v4u o; o.x = pk2(s[0 * 65] * s0.x, s[1 * 65] * s0.y); o.y = pk2(s[2 * 65] * s0.z, s[3 * 65] * s0.w); o.z = pk2(s[4 * 65] * s1.x, s[5 * 65] * s1.y); o.w = pk2(s[6 * 65] * s1.z, s[7 * 65] * s1.w);
;         if (!(variant & 4)) *(GAS v4u*)(t.dst + (size_t)(t.drow0 + nn) * t.Kd + t.k0 + 8 * c) = o;
;         else asm volatile("" :: "v"(o));
;     }
;     LDS_WAIT(); asm volatile("" ::: "memory");
.LBB0_583:
	ds_write2_b32 v161, v76, v77 offset1:1
	ds_write2_b32 v161, v78, v79 offset0:2 offset1:3
	ds_write2_b32 v172, v84, v85 offset1:1
	ds_write2_b32 v173, v86, v87 offset1:1
	ds_write2_b32 v174, v88, v89 offset1:1
	ds_write2_b32 v175, v90, v91 offset1:1
	ds_write2_b32 v176, v92, v93 offset1:1
	ds_write2_b32 v177, v94, v95 offset1:1
	ds_write2_b32 v178, v104, v105 offset1:1
	ds_write2_b32 v179, v106, v107 offset1:1
	ds_write2_b32 v180, v108, v109 offset1:1
	ds_write2_b32 v181, v110, v111 offset1:1
	ds_write2_b32 v186, v112, v113 offset1:1
	ds_write2_b32 v187, v114, v115 offset1:1
	ds_write2_b32 v188, v116, v117 offset1:1
	ds_write2_b32 v189, v118, v119 offset1:1
	ds_write2_b32 v190, v120, v121 offset1:1
	ds_write2_b32 v191, v122, v123 offset1:1
	ds_write2_b32 v192, v124, v125 offset1:1
	ds_write2_b32 v193, v126, v127 offset1:1
	ds_write2_b32 v194, v128, v129 offset1:1
	ds_write2_b32 v195, v130, v131 offset1:1
	ds_write2_b32 v196, v132, v133 offset1:1
	ds_write2_b32 v197, v134, v135 offset1:1
	ds_write2_b32 v198, v136, v137 offset1:1
	ds_write2_b32 v199, v138, v139 offset1:1
	ds_write2_b32 v200, v144, v145 offset1:1
	ds_write2_b32 v201, v146, v147 offset1:1
	ds_write2_b32 v202, v140, v141 offset1:1
	ds_write2_b32 v203, v142, v143 offset1:1
	ds_write2_b32 v204, v148, v149 offset1:1
	ds_write2_b32 v205, v150, v151 offset1:1
	s_waitcnt lgkmcnt(0)
	ds_read2_b32 v[98:99], v163 offset1:8
	ds_read2_b32 v[102:103], v163 offset0:65 offset1:73
	ds_read2_b32 v[176:177], v163 offset0:130 offset1:138
	ds_read2_b32 v[178:179], v163 offset0:195 offset1:203
	ds_read2_b32 v[180:181], v171 offset0:4 offset1:12
	ds_read2_b32 v[186:187], v171 offset0:69 offset1:77
	ds_read2_b32 v[188:189], v171 offset0:134 offset1:142
	ds_read2_b32 v[190:191], v171 offset0:199 offset1:207
	s_waitcnt lgkmcnt(7)
	v_mov_b32_e32 v172, v98
	s_waitcnt lgkmcnt(6)
	v_mov_b32_e32 v173, v102
	s_waitcnt lgkmcnt(5)
	v_mov_b32_e32 v174, v176
	s_waitcnt lgkmcnt(4)
	v_mov_b32_e32 v175, v178
	v_pk_mul_f32 v[172:173], v[60:61], v[172:173]
	v_pk_mul_f32 v[174:175], v[62:63], v[174:175]
	v_cvt_pk_bf16_f32 v172, v172, v173
	v_cvt_pk_bf16_f32 v173, v174, v175
	s_waitcnt lgkmcnt(3)
	v_mov_b32_e32 v174, v180
	s_waitcnt lgkmcnt(2)
	v_mov_b32_e32 v175, v186
	s_waitcnt lgkmcnt(1)
	v_mov_b32_e32 v192, v188
	s_waitcnt lgkmcnt(0)
	v_mov_b32_e32 v193, v190
	v_pk_mul_f32 v[174:175], v[56:57], v[174:175]
	v_pk_mul_f32 v[192:193], v[58:59], v[192:193]
	v_add_u32_e32 v96, s67, v162
	v_cvt_pk_bf16_f32 v174, v174, v175
	v_cvt_pk_bf16_f32 v175, v192, v193
	v_mad_i64_i32 v[192:193], s[48:49], s68, v96, 0
	s_ashr_i32 s45, s44, 31
	v_lshl_add_u64 v[192:193], v[192:193], 1, v[158:159]
	s_lshl_b64 s[48:49], s[44:45], 1
	v_lshl_add_u64 v[192:193], v[192:193], 0, s[48:49]
	v_mov_b32_e32 v157, v97
	v_mov_b32_e32 v102, v99
	v_lshl_add_u64 v[192:193], v[192:193], 0, v[156:157]
	v_pk_mul_f32 v[98:99], v[60:61], v[102:103]
	v_mov_b32_e32 v178, v177
	global_store_dwordx4 v[192:193], v[172:175], off sc1
	v_mov_b32_e32 v186, v181
	v_mov_b32_e32 v190, v189
	v_cvt_pk_bf16_f32 v172, v98, v99
	v_pk_mul_f32 v[98:99], v[62:63], v[178:179]
	v_add_u32_e32 v96, s67, v164
	v_cvt_pk_bf16_f32 v173, v98, v99
	v_pk_mul_f32 v[98:99], v[56:57], v[186:187]
	ds_read2_b32 v[102:103], v163 offset0:16 offset1:24
	v_cvt_pk_bf16_f32 v174, v98, v99
	v_pk_mul_f32 v[98:99], v[58:59], v[190:191]
	ds_read2_b32 v[176:177], v163 offset0:81 offset1:89
	v_cvt_pk_bf16_f32 v175, v98, v99
	v_mad_i64_i32 v[98:99], s[50:51], s68, v96, 0
	v_lshl_add_u64 v[98:99], v[98:99], 1, v[158:159]
	ds_read2_b32 v[178:179], v163 offset0:146 offset1:154
	ds_read2_b32 v[180:181], v163 offset0:211 offset1:219
	v_lshl_add_u64 v[98:99], v[98:99], 0, s[48:49]
	v_lshl_add_u64 v[98:99], v[98:99], 0, v[156:157]
	ds_read2_b32 v[186:187], v171 offset0:20 offset1:28
	ds_read2_b32 v[188:189], v171 offset0:85 offset1:93
	global_store_dwordx4 v[98:99], v[172:175], off sc1
	s_waitcnt lgkmcnt(5)
	v_mov_b32_e32 v98, v102
	s_waitcnt lgkmcnt(4)
	v_mov_b32_e32 v99, v176
	v_pk_mul_f32 v[98:99], v[60:61], v[98:99]
	ds_read2_b32 v[190:191], v171 offset0:150 offset1:158
	ds_read2_b32 v[192:193], v171 offset0:215 offset1:223
	v_cvt_pk_bf16_f32 v172, v98, v99
	s_waitcnt lgkmcnt(5)
	v_mov_b32_e32 v98, v178
	s_waitcnt lgkmcnt(4)
	v_mov_b32_e32 v99, v180
	v_pk_mul_f32 v[98:99], v[62:63], v[98:99]
	v_add_u32_e32 v96, s67, v165
	v_cvt_pk_bf16_f32 v173, v98, v99
	s_waitcnt lgkmcnt(3)
	v_mov_b32_e32 v98, v186
	s_waitcnt lgkmcnt(2)
	v_mov_b32_e32 v99, v188
	v_pk_mul_f32 v[98:99], v[56:57], v[98:99]
	v_mov_b32_e32 v176, v103
	v_cvt_pk_bf16_f32 v174, v98, v99
	s_waitcnt lgkmcnt(1)
	v_mov_b32_e32 v98, v190
	s_waitcnt lgkmcnt(0)
; #define GAS __attribute__((address_space(1)))
; #define LAS __attribute__((address_space(3)))
; #define LDS_WAIT() asm volatile("s_waitcnt lgkmcnt(0)" ::: "memory")
; DI unsigned pk2(float lo, float hi) { f32x2 v = {lo, hi}; bf16x2_t b = __builtin_convertvector(v, bf16x2_t); return __builtin_bit_cast(unsigned, b); }
;     ...
;     for (int j = 0; j < 8; ++j) {
;         const int nn = (lane >> 3) + 8 * j; const LAS float* s = scr + (8 * c) * 65 + nn;
;         v4u o; o.x = pk2(s[0 * 65] * s0.x, s[1 * 65] * s0.y); o.y = pk2(s[2 * 65] * s0.z, s[3 * 65] * s0.w); o.z = pk2(s[4 * 65] * s1.x, s[5 * 65] * s1.y); o.w = pk2(s[6 * 65] * s1.z, s[7 * 65] * s1.w);
;         if (!(variant & 4)) *(GAS v4u*)(t.dst + (size_t)(t.drow0 + nn) * t.Kd + t.k0 + 8 * c) = o;
;         else asm volatile("" :: "v"(o));
;     }
;     LDS_WAIT(); asm volatile("" ::: "memory");
	v_mov_b32_e32 v99, v192
	v_pk_mul_f32 v[98:99], v[58:59], v[98:99]
	v_mov_b32_e32 v180, v179
	v_cvt_pk_bf16_f32 v175, v98, v99
	v_mad_i64_i32 v[98:99], s[50:51], s68, v96, 0
	v_lshl_add_u64 v[98:99], v[98:99], 1, v[158:159]
	v_lshl_add_u64 v[98:99], v[98:99], 0, s[48:49]
	v_lshl_add_u64 v[98:99], v[98:99], 0, v[156:157]
	global_store_dwordx4 v[98:99], v[172:175], off sc1
	v_pk_mul_f32 v[98:99], v[60:61], v[176:177]
	v_mov_b32_e32 v188, v187
	v_cvt_pk_bf16_f32 v172, v98, v99
	v_pk_mul_f32 v[98:99], v[62:63], v[180:181]
	v_mov_b32_e32 v192, v191
	v_cvt_pk_bf16_f32 v173, v98, v99
	v_pk_mul_f32 v[98:99], v[56:57], v[188:189]
	v_add_u32_e32 v96, s67, v166
	v_cvt_pk_bf16_f32 v174, v98, v99
	v_pk_mul_f32 v[98:99], v[58:59], v[192:193]
	ds_read2_b32 v[102:103], v163 offset0:32 offset1:40
	ds_read2_b32 v[176:177], v163 offset0:97 offset1:105
	v_cvt_pk_bf16_f32 v175, v98, v99
	v_mad_i64_i32 v[98:99], s[50:51], s68, v96, 0
	v_lshl_add_u64 v[98:99], v[98:99], 1, v[158:159]
	ds_read2_b32 v[178:179], v163 offset0:162 offset1:170
	ds_read2_b32 v[180:181], v163 offset0:227 offset1:235
	v_lshl_add_u64 v[98:99], v[98:99], 0, s[48:49]
	v_lshl_add_u64 v[98:99], v[98:99], 0, v[156:157]
	ds_read2_b32 v[186:187], v171 offset0:36 offset1:44
	ds_read2_b32 v[188:189], v171 offset0:101 offset1:109
	global_store_dwordx4 v[98:99], v[172:175], off sc1
	s_waitcnt lgkmcnt(5)
	v_mov_b32_e32 v98, v102
	s_waitcnt lgkmcnt(4)
	v_mov_b32_e32 v99, v176
	v_pk_mul_f32 v[98:99], v[60:61], v[98:99]
	ds_read2_b32 v[190:191], v171 offset0:166 offset1:174
	ds_read2_b32 v[192:193], v171 offset0:231 offset1:239
	v_cvt_pk_bf16_f32 v172, v98, v99
	s_waitcnt lgkmcnt(5)
	v_mov_b32_e32 v98, v178
	s_waitcnt lgkmcnt(4)
	v_mov_b32_e32 v99, v180
	v_pk_mul_f32 v[98:99], v[62:63], v[98:99]
	v_add_u32_e32 v96, s67, v167
	v_cvt_pk_bf16_f32 v173, v98, v99
	s_waitcnt lgkmcnt(3)
	v_mov_b32_e32 v98, v186
	s_waitcnt lgkmcnt(2)
	v_mov_b32_e32 v99, v188
	v_pk_mul_f32 v[98:99], v[56:57], v[98:99]
	v_mov_b32_e32 v176, v103
	v_cvt_pk_bf16_f32 v174, v98, v99
	s_waitcnt lgkmcnt(1)
	v_mov_b32_e32 v98, v190
	s_waitcnt lgkmcnt(0)
	v_mov_b32_e32 v99, v192
	v_pk_mul_f32 v[98:99], v[58:59], v[98:99]
	v_mov_b32_e32 v180, v179
	v_cvt_pk_bf16_f32 v175, v98, v99
	v_mad_i64_i32 v[98:99], s[50:51], s68, v96, 0
	v_lshl_add_u64 v[98:99], v[98:99], 1, v[158:159]
	v_lshl_add_u64 v[98:99], v[98:99], 0, s[48:49]
	v_lshl_add_u64 v[98:99], v[98:99], 0, v[156:157]
	global_store_dwordx4 v[98:99], v[172:175], off sc1
	v_pk_mul_f32 v[98:99], v[60:61], v[176:177]
	v_mov_b32_e32 v188, v187
	v_cvt_pk_bf16_f32 v172, v98, v99
	v_pk_mul_f32 v[98:99], v[62:63], v[180:181]
	v_mov_b32_e32 v192, v191
	v_cvt_pk_bf16_f32 v173, v98, v99
	v_pk_mul_f32 v[98:99], v[56:57], v[188:189]
	v_add_u32_e32 v96, s67, v168
	v_cvt_pk_bf16_f32 v174, v98, v99
	v_pk_mul_f32 v[98:99], v[58:59], v[192:193]
	ds_read2_b32 v[102:103], v163 offset0:48 offset1:56
	ds_read2_b32 v[176:177], v163 offset0:113 offset1:121
	v_cvt_pk_bf16_f32 v175, v98, v99
	v_mad_i64_i32 v[98:99], s[50:51], s68, v96, 0
	v_lshl_add_u64 v[98:99], v[98:99], 1, v[158:159]
	ds_read2_b32 v[178:179], v163 offset0:178 offset1:186
	ds_read2_b32 v[180:181], v163 offset0:243 offset1:251
	v_lshl_add_u64 v[98:99], v[98:99], 0, s[48:49]
	v_lshl_add_u64 v[98:99], v[98:99], 0, v[156:157]
	ds_read2_b32 v[186:187], v171 offset0:52 offset1:60
	ds_read2_b32 v[188:189], v171 offset0:117 offset1:125
	global_store_dwordx4 v[98:99], v[172:175], off sc1
	s_waitcnt lgkmcnt(5)
	v_mov_b32_e32 v98, v102
	s_waitcnt lgkmcnt(4)
	v_mov_b32_e32 v99, v176
	v_pk_mul_f32 v[98:99], v[60:61], v[98:99]
	ds_read2_b32 v[190:191], v171 offset0:182 offset1:190
	ds_read2_b32 v[192:193], v171 offset0:247 offset1:255
	v_cvt_pk_bf16_f32 v172, v98, v99
	s_waitcnt lgkmcnt(5)
	v_mov_b32_e32 v98, v178
	s_waitcnt lgkmcnt(4)
	v_mov_b32_e32 v99, v180
	v_pk_mul_f32 v[98:99], v[62:63], v[98:99]
	v_add_u32_e32 v96, s67, v169
	v_cvt_pk_bf16_f32 v173, v98, v99
	s_waitcnt lgkmcnt(3)
	v_mov_b32_e32 v98, v186
	s_waitcnt lgkmcnt(2)
	v_mov_b32_e32 v99, v188
	v_pk_mul_f32 v[98:99], v[56:57], v[98:99]
	v_mov_b32_e32 v176, v103
	v_cvt_pk_bf16_f32 v174, v98, v99
	s_waitcnt lgkmcnt(1)
	v_mov_b32_e32 v98, v190
	s_waitcnt lgkmcnt(0)
	v_mov_b32_e32 v99, v192
	v_pk_mul_f32 v[98:99], v[58:59], v[98:99]
	v_mov_b32_e32 v180, v179
	v_cvt_pk_bf16_f32 v175, v98, v99
	v_mad_i64_i32 v[98:99], s[50:51], s68, v96, 0
	v_lshl_add_u64 v[98:99], v[98:99], 1, v[158:159]
	v_lshl_add_u64 v[98:99], v[98:99], 0, s[48:49]
	v_lshl_add_u64 v[98:99], v[98:99], 0, v[156:157]
	global_store_dwordx4 v[98:99], v[172:175], off sc1
	v_pk_mul_f32 v[98:99], v[60:61], v[176:177]
	v_mov_b32_e32 v188, v187
	v_cvt_pk_bf16_f32 v172, v98, v99
	v_pk_mul_f32 v[98:99], v[62:63], v[180:181]
	v_mov_b32_e32 v192, v191
	v_cvt_pk_bf16_f32 v173, v98, v99
	v_pk_mul_f32 v[98:99], v[56:57], v[188:189]
	v_add_u32_e32 v96, s67, v170
	v_cvt_pk_bf16_f32 v174, v98, v99
	v_pk_mul_f32 v[98:99], v[58:59], v[192:193]
	s_nop 0
	v_cvt_pk_bf16_f32 v175, v98, v99
	v_mad_i64_i32 v[98:99], s[50:51], s68, v96, 0
	v_lshl_add_u64 v[98:99], v[98:99], 1, v[158:159]
	v_lshl_add_u64 v[98:99], v[98:99], 0, s[48:49]
	v_lshl_add_u64 v[98:99], v[98:99], 0, v[156:157]
	global_store_dwordx4 v[98:99], v[172:175], off sc1
	s_waitcnt lgkmcnt(0)

; #define GAS __attribute__((address_space(1)))
; #define LAS __attribute__((address_space(3)))
; #define LDS_WAIT() asm volatile("s_waitcnt lgkmcnt(0)" ::: "memory")
; DI unsigned pk2(float lo, float hi) { f32x2 v = {lo, hi}; bf16x2_t b = __builtin_convertvector(v, bf16x2_t); return __builtin_bit_cast(unsigned, b); }
;     ...
;         LAS float* w = scr + (lane >> 4) * 65 + 4 * (lane & 15);
; #pragma unroll
;         for (int i = 0; i < 16; ++i) { w[(4 * i) * 65 + 0] = v[i].x; w[(4 * i) * 65 + 1] = v[i].y; w[(4 * i) * 65 + 2] = v[i].z; w[(4 * i) * 65 + 3] = v[i].w; }
;     }
;     LDS_WAIT(); asm volatile("" ::: "memory");
;     const int c = lane & 7;
;     const f32x4 s0 = sc[0], s1 = sc[1];
; #pragma unroll
;     for (int j = 0; j < 8; ++j) {
;         const int nn = (lane >> 3) + 8 * j; const LAS float* s = scr + (8 * c) * 65 + nn;
;         v4u o; o.x = pk2(s[0 * 65] * s0.x, s[1 * 65] * s0.y); o.y = pk2(s[2 * 65] * s0.z, s[3 * 65] * s0.w); o.z = pk2(s[4 * 65] * s1.x, s[5 * 65] * s1.y); o.w = pk2(s[6 * 65] * s1.z, s[7 * 65] * s1.w);
;         if (!(variant & 4)) *(GAS v4u*)(t.dst + (size_t)(t.drow0 + nn) * t.Kd + t.k0 + 8 * c) = o;
;         else asm volatile("" :: "v"(o));
;     }
;     LDS_WAIT(); asm volatile("" ::: "memory");
.LBB0_621:
	v_add_u32_e32 v172, 0x410, v161
	v_add_u32_e32 v173, 0x418, v161
	v_add_u32_e32 v174, 0x820, v161
	v_add_u32_e32 v175, 0x828, v161
	v_add_u32_e32 v176, 0xc30, v161
	v_add_u32_e32 v177, 0xc38, v161
	v_add_u32_e32 v178, 0x1040, v161
	v_add_u32_e32 v179, 0x1048, v161
	v_add_u32_e32 v180, 0x1450, v161
	v_add_u32_e32 v181, 0x1458, v161
	v_add_u32_e32 v186, 0x1860, v161
	v_add_u32_e32 v187, 0x1868, v161
	v_add_u32_e32 v188, 0x1c70, v161
	v_add_u32_e32 v189, 0x1c78, v161
	v_add_u32_e32 v190, 0x2080, v161
	v_add_u32_e32 v191, 0x2088, v161
	v_add_u32_e32 v192, 0x2490, v161
	v_add_u32_e32 v193, 0x2498, v161
	v_add_u32_e32 v194, 0x28a0, v161
	v_add_u32_e32 v195, 0x28a8, v161
	v_add_u32_e32 v196, 0x2cb0, v161
	v_add_u32_e32 v197, 0x2cb8, v161
	v_add_u32_e32 v198, 0x30c0, v161
	v_add_u32_e32 v199, 0x30c8, v161
	v_add_u32_e32 v200, 0x34d0, v161
	v_add_u32_e32 v201, 0x34d8, v161
	v_add_u32_e32 v202, 0x38e0, v161
	v_add_u32_e32 v203, 0x38e8, v161
	v_add_u32_e32 v204, 0x3cf0, v161
	v_add_u32_e32 v205, 0x3cf8, v161
	s_waitcnt vmcnt(0)
	ds_write2_b32 v161, v8, v9 offset1:1
	ds_write2_b32 v161, v10, v11 offset0:2 offset1:3
	ds_write2_b32 v172, v12, v13 offset1:1
	ds_write2_b32 v173, v14, v15 offset1:1
	ds_write2_b32 v174, v16, v17 offset1:1
	ds_write2_b32 v175, v18, v19 offset1:1
	ds_write2_b32 v176, v20, v21 offset1:1
	ds_write2_b32 v177, v22, v23 offset1:1
	ds_write2_b32 v178, v24, v25 offset1:1
	ds_write2_b32 v179, v26, v27 offset1:1
	ds_write2_b32 v180, v28, v29 offset1:1
	ds_write2_b32 v181, v30, v31 offset1:1
	ds_write2_b32 v186, v32, v33 offset1:1
	ds_write2_b32 v187, v34, v35 offset1:1
	ds_write2_b32 v188, v36, v37 offset1:1
	ds_write2_b32 v189, v38, v39 offset1:1
	ds_write2_b32 v190, v40, v41 offset1:1
	ds_write2_b32 v191, v42, v43 offset1:1
	ds_write2_b32 v192, v44, v45 offset1:1
	ds_write2_b32 v193, v46, v47 offset1:1
	ds_write2_b32 v194, v48, v49 offset1:1
	ds_write2_b32 v195, v50, v51 offset1:1
	ds_write2_b32 v196, v52, v53 offset1:1
	ds_write2_b32 v197, v54, v55 offset1:1
	ds_write2_b32 v198, v64, v65 offset1:1
	ds_write2_b32 v199, v66, v67 offset1:1
	ds_write2_b32 v200, v68, v69 offset1:1
	ds_write2_b32 v201, v70, v71 offset1:1
	ds_write2_b32 v202, v72, v73 offset1:1
	ds_write2_b32 v203, v74, v75 offset1:1
	ds_write2_b32 v204, v80, v81 offset1:1
	ds_write2_b32 v205, v82, v83 offset1:1
	s_waitcnt lgkmcnt(0)
	ds_read2_b32 v[98:99], v163 offset1:8
	ds_read2_b32 v[102:103], v163 offset0:65 offset1:73
	ds_read2_b32 v[210:211], v163 offset0:130 offset1:138
	ds_read2_b32 v[212:213], v163 offset0:195 offset1:203
	v_add_u32_e32 v171, 0x400, v163
	ds_read2_b32 v[214:215], v171 offset0:4 offset1:12
	ds_read2_b32 v[216:217], v171 offset0:69 offset1:77
	ds_read2_b32 v[218:219], v171 offset0:134 offset1:142
	ds_read2_b32 v[220:221], v171 offset0:199 offset1:207
	s_waitcnt lgkmcnt(0)
	v_mov_b32_e32 v206, v98
	v_mov_b32_e32 v207, v102
	v_mov_b32_e32 v208, v210
	v_mov_b32_e32 v209, v212
	v_pk_mul_f32 v[206:207], v[4:5], v[206:207]
	v_pk_mul_f32 v[208:209], v[6:7], v[208:209]
	v_cvt_pk_bf16_f32 v206, v206, v207
	v_cvt_pk_bf16_f32 v207, v208, v209
	v_mov_b32_e32 v208, v214
	v_mov_b32_e32 v209, v216
	v_mov_b32_e32 v222, v218
	v_mov_b32_e32 v223, v220
	v_pk_mul_f32 v[208:209], v[0:1], v[208:209]
	v_pk_mul_f32 v[222:223], v[2:3], v[222:223]
	v_add_u32_e32 v96, s38, v162
	v_cvt_pk_bf16_f32 v208, v208, v209
	v_cvt_pk_bf16_f32 v209, v222, v223
	v_mad_i64_i32 v[222:223], s[48:49], s63, v96, 0
	s_ashr_i32 s31, s30, 31
	v_lshl_add_u64 v[222:223], v[222:223], 1, v[152:153]
	s_lshl_b64 s[48:49], s[30:31], 1
	v_lshl_add_u64 v[222:223], v[222:223], 0, s[48:49]
	v_mov_b32_e32 v157, v97
	v_mov_b32_e32 v102, v99
	v_lshl_add_u64 v[222:223], v[222:223], 0, v[156:157]
	v_pk_mul_f32 v[98:99], v[4:5], v[102:103]
	v_mov_b32_e32 v212, v211
	global_store_dwordx4 v[222:223], v[206:209], off sc1
	v_mov_b32_e32 v216, v215
	v_mov_b32_e32 v220, v219
	v_cvt_pk_bf16_f32 v206, v98, v99
	v_pk_mul_f32 v[98:99], v[6:7], v[212:213]
	v_add_u32_e32 v96, s38, v164
	v_cvt_pk_bf16_f32 v207, v98, v99
	v_pk_mul_f32 v[98:99], v[0:1], v[216:217]
	ds_read2_b32 v[102:103], v163 offset0:16 offset1:24
	v_cvt_pk_bf16_f32 v208, v98, v99
	v_pk_mul_f32 v[98:99], v[2:3], v[220:221]
	ds_read2_b32 v[210:211], v163 offset0:81 offset1:89
	v_cvt_pk_bf16_f32 v209, v98, v99
	v_mad_i64_i32 v[98:99], s[50:51], s63, v96, 0
	v_lshl_add_u64 v[98:99], v[98:99], 1, v[152:153]
	ds_read2_b32 v[212:213], v163 offset0:146 offset1:154
	ds_read2_b32 v[214:215], v163 offset0:211 offset1:219
	v_lshl_add_u64 v[98:99], v[98:99], 0, s[48:49]
	v_lshl_add_u64 v[98:99], v[98:99], 0, v[156:157]
	ds_read2_b32 v[216:217], v171 offset0:20 offset1:28
	ds_read2_b32 v[218:219], v171 offset0:85 offset1:93
	global_store_dwordx4 v[98:99], v[206:209], off sc1
	s_waitcnt lgkmcnt(5)
	v_mov_b32_e32 v98, v102
	s_waitcnt lgkmcnt(4)
	v_mov_b32_e32 v99, v210
	v_pk_mul_f32 v[98:99], v[4:5], v[98:99]
	ds_read2_b32 v[220:221], v171 offset0:150 offset1:158
	ds_read2_b32 v[222:223], v171 offset0:215 offset1:223
	v_cvt_pk_bf16_f32 v206, v98, v99
	s_waitcnt lgkmcnt(5)
	v_mov_b32_e32 v98, v212
	s_waitcnt lgkmcnt(4)
	v_mov_b32_e32 v99, v214
	v_pk_mul_f32 v[98:99], v[6:7], v[98:99]
	v_add_u32_e32 v96, s38, v165
	v_cvt_pk_bf16_f32 v207, v98, v99
	s_waitcnt lgkmcnt(3)
	v_mov_b32_e32 v98, v216
	s_waitcnt lgkmcnt(2)
	v_mov_b32_e32 v99, v218
	v_pk_mul_f32 v[98:99], v[0:1], v[98:99]
	v_mov_b32_e32 v210, v103
	v_cvt_pk_bf16_f32 v208, v98, v99
	s_waitcnt lgkmcnt(1)
	v_mov_b32_e32 v98, v220
	s_waitcnt lgkmcnt(0)
; #define GAS __attribute__((address_space(1)))
; #define LAS __attribute__((address_space(3)))
; #define LDS_WAIT() asm volatile("s_waitcnt lgkmcnt(0)" ::: "memory")
; DI unsigned pk2(float lo, float hi) { f32x2 v = {lo, hi}; bf16x2_t b = __builtin_convertvector(v, bf16x2_t); return __builtin_bit_cast(unsigned, b); }
; DI void tr_decode(const Frame& F, int git, TrItem& t) {
;     const int l = git / I_LAYER; int r = git - l * I_LAYER;
;     int s = 0;
;     if (r >= 3 * I_G + I_IN + I_OUT) { s = 1; r -= 3 * I_G + I_IN + I_OUT; }
;     if (r < 3 * I_G) {
;         const int kind = r / I_G; r -= kind * I_G; const int f = 2 * l + s;
;         if (kind < 2) {
;             const int up = kind;
;             t.W = F.in[s ? (up ? 21 : 20) : (up ? 3 : 2)] + (size_t)l * D * DFF; t.sc = F.in[s ? 19 : 1] + l * D;
;             const int kb = r / (DFF / 64), nb = r % (DFF / 64); t.k0 = 64 * kb; t.n0 = 64 * nb; t.N = DFF; t.Kd = D;
;             t.dst = (bf16*)(F.ws + WS_WGU + (size_t)f * SZ_WGU1); t.drow0 = 256 * (t.n0 >> 7) + (t.n0 & 127) + (up ? 128 : 0);
;         } else {
;             t.W = F.in[s ? 22 : 4] + (size_t)l * DFF * D; t.sc = nullptr;
;             const int kb = r / (D / 64), nb = r % (D / 64); t.k0 = 64 * kb; t.n0 = 64 * nb; t.N = D; t.Kd = DFF;
;             t.dst = (bf16*)(F.ws + WS_WD + (size_t)f * SZ_WD1); t.drow0 = t.n0;
;         }
;         return;
;     }
;     r -= 3 * I_G;
;     if (r < I_IN) {
;         t.W = F.in[6] + (size_t)l * D * DIN; t.sc = F.in[5] + l * D;
;         const int kb = r / 121, nb = r % 121; t.k0 = 64 * kb; t.n0 = 64 * nb; t.N = DIN; t.Kd = D;
;         t.dst = (bf16*)(F.ws + WS_WIN + (size_t)l * SZ_WIN1); t.drow0 = t.n0;
;         return;
;     }
;     r -= I_IN;
;     ...
;     for (int j = 0; j < 8; ++j) {
;         const int nn = (lane >> 3) + 8 * j; const LAS float* s = scr + (8 * c) * 65 + nn;
;         v4u o; o.x = pk2(s[0 * 65] * s0.x, s[1 * 65] * s0.y); o.y = pk2(s[2 * 65] * s0.z, s[3 * 65] * s0.w); o.z = pk2(s[4 * 65] * s1.x, s[5 * 65] * s1.y); o.w = pk2(s[6 * 65] * s1.z, s[7 * 65] * s1.w);
;         if (!(variant & 4)) *(GAS v4u*)(t.dst + (size_t)(t.drow0 + nn) * t.Kd + t.k0 + 8 * c) = o;
;         else asm volatile("" :: "v"(o));
;     }
;     LDS_WAIT(); asm volatile("" ::: "memory");
	v_mov_b32_e32 v99, v222
	v_pk_mul_f32 v[98:99], v[2:3], v[98:99]
	v_mov_b32_e32 v214, v213
	v_cvt_pk_bf16_f32 v209, v98, v99
	v_mad_i64_i32 v[98:99], s[50:51], s63, v96, 0
	v_lshl_add_u64 v[98:99], v[98:99], 1, v[152:153]
	v_lshl_add_u64 v[98:99], v[98:99], 0, s[48:49]
	v_lshl_add_u64 v[98:99], v[98:99], 0, v[156:157]
	global_store_dwordx4 v[98:99], v[206:209], off sc1
	v_pk_mul_f32 v[98:99], v[4:5], v[210:211]
	v_mov_b32_e32 v218, v217
	v_cvt_pk_bf16_f32 v206, v98, v99
	v_pk_mul_f32 v[98:99], v[6:7], v[214:215]
	v_mov_b32_e32 v222, v221
	v_cvt_pk_bf16_f32 v207, v98, v99
	v_pk_mul_f32 v[98:99], v[0:1], v[218:219]
	v_add_u32_e32 v96, s38, v166
	v_cvt_pk_bf16_f32 v208, v98, v99
	v_pk_mul_f32 v[98:99], v[2:3], v[222:223]
	ds_read2_b32 v[102:103], v163 offset0:32 offset1:40
	ds_read2_b32 v[210:211], v163 offset0:97 offset1:105
	v_cvt_pk_bf16_f32 v209, v98, v99
	v_mad_i64_i32 v[98:99], s[50:51], s63, v96, 0
	v_lshl_add_u64 v[98:99], v[98:99], 1, v[152:153]
	ds_read2_b32 v[212:213], v163 offset0:162 offset1:170
	ds_read2_b32 v[214:215], v163 offset0:227 offset1:235
	v_lshl_add_u64 v[98:99], v[98:99], 0, s[48:49]
	v_lshl_add_u64 v[98:99], v[98:99], 0, v[156:157]
	ds_read2_b32 v[216:217], v171 offset0:36 offset1:44
	ds_read2_b32 v[218:219], v171 offset0:101 offset1:109
	global_store_dwordx4 v[98:99], v[206:209], off sc1
	s_waitcnt lgkmcnt(5)
	v_mov_b32_e32 v98, v102
	s_waitcnt lgkmcnt(4)
	v_mov_b32_e32 v99, v210
	v_pk_mul_f32 v[98:99], v[4:5], v[98:99]
	ds_read2_b32 v[220:221], v171 offset0:166 offset1:174
	ds_read2_b32 v[222:223], v171 offset0:231 offset1:239
	v_cvt_pk_bf16_f32 v206, v98, v99
	s_waitcnt lgkmcnt(5)
	v_mov_b32_e32 v98, v212
	s_waitcnt lgkmcnt(4)
	v_mov_b32_e32 v99, v214
	v_pk_mul_f32 v[98:99], v[6:7], v[98:99]
	v_add_u32_e32 v96, s38, v167
	v_cvt_pk_bf16_f32 v207, v98, v99
	s_waitcnt lgkmcnt(3)
	v_mov_b32_e32 v98, v216
	s_waitcnt lgkmcnt(2)
	v_mov_b32_e32 v99, v218
	v_pk_mul_f32 v[98:99], v[0:1], v[98:99]
	v_mov_b32_e32 v210, v103
	v_cvt_pk_bf16_f32 v208, v98, v99
	s_waitcnt lgkmcnt(1)
	v_mov_b32_e32 v98, v220
	s_waitcnt lgkmcnt(0)
	v_mov_b32_e32 v99, v222
	v_pk_mul_f32 v[98:99], v[2:3], v[98:99]
	v_mov_b32_e32 v214, v213
	v_cvt_pk_bf16_f32 v209, v98, v99
	v_mad_i64_i32 v[98:99], s[50:51], s63, v96, 0
	v_lshl_add_u64 v[98:99], v[98:99], 1, v[152:153]
	v_lshl_add_u64 v[98:99], v[98:99], 0, s[48:49]
	v_lshl_add_u64 v[98:99], v[98:99], 0, v[156:157]
	global_store_dwordx4 v[98:99], v[206:209], off sc1
	v_pk_mul_f32 v[98:99], v[4:5], v[210:211]
	v_mov_b32_e32 v218, v217
	v_cvt_pk_bf16_f32 v206, v98, v99
	v_pk_mul_f32 v[98:99], v[6:7], v[214:215]
	v_mov_b32_e32 v222, v221
	v_cvt_pk_bf16_f32 v207, v98, v99
	v_pk_mul_f32 v[98:99], v[0:1], v[218:219]
	v_add_u32_e32 v96, s38, v168
	v_cvt_pk_bf16_f32 v208, v98, v99
	v_pk_mul_f32 v[98:99], v[2:3], v[222:223]
	ds_read2_b32 v[102:103], v163 offset0:48 offset1:56
	ds_read2_b32 v[210:211], v163 offset0:113 offset1:121
	v_cvt_pk_bf16_f32 v209, v98, v99
	v_mad_i64_i32 v[98:99], s[50:51], s63, v96, 0
	v_lshl_add_u64 v[98:99], v[98:99], 1, v[152:153]
	ds_read2_b32 v[212:213], v163 offset0:178 offset1:186
	ds_read2_b32 v[214:215], v163 offset0:243 offset1:251
	v_lshl_add_u64 v[98:99], v[98:99], 0, s[48:49]
	v_lshl_add_u64 v[98:99], v[98:99], 0, v[156:157]
	ds_read2_b32 v[216:217], v171 offset0:52 offset1:60
	ds_read2_b32 v[218:219], v171 offset0:117 offset1:125
	global_store_dwordx4 v[98:99], v[206:209], off sc1
	s_waitcnt lgkmcnt(5)
	v_mov_b32_e32 v98, v102
	s_waitcnt lgkmcnt(4)
	v_mov_b32_e32 v99, v210
	v_pk_mul_f32 v[98:99], v[4:5], v[98:99]
	ds_read2_b32 v[220:221], v171 offset0:182 offset1:190
	ds_read2_b32 v[222:223], v171 offset0:247 offset1:255
	v_cvt_pk_bf16_f32 v206, v98, v99
	s_waitcnt lgkmcnt(5)
	v_mov_b32_e32 v98, v212
	s_waitcnt lgkmcnt(4)
	v_mov_b32_e32 v99, v214
	v_pk_mul_f32 v[98:99], v[6:7], v[98:99]
	v_add_u32_e32 v96, s38, v169
	v_cvt_pk_bf16_f32 v207, v98, v99
	s_waitcnt lgkmcnt(3)
	v_mov_b32_e32 v98, v216
	s_waitcnt lgkmcnt(2)
	v_mov_b32_e32 v99, v218
	v_pk_mul_f32 v[98:99], v[0:1], v[98:99]
	v_mov_b32_e32 v210, v103
	v_cvt_pk_bf16_f32 v208, v98, v99
	s_waitcnt lgkmcnt(1)
	v_mov_b32_e32 v98, v220
	s_waitcnt lgkmcnt(0)
	v_mov_b32_e32 v99, v222
	v_pk_mul_f32 v[98:99], v[2:3], v[98:99]
	v_mov_b32_e32 v214, v213
	v_cvt_pk_bf16_f32 v209, v98, v99
	v_mad_i64_i32 v[98:99], s[50:51], s63, v96, 0
	v_lshl_add_u64 v[98:99], v[98:99], 1, v[152:153]
	v_lshl_add_u64 v[98:99], v[98:99], 0, s[48:49]
	v_lshl_add_u64 v[98:99], v[98:99], 0, v[156:157]
	global_store_dwordx4 v[98:99], v[206:209], off sc1
	v_pk_mul_f32 v[98:99], v[4:5], v[210:211]
	v_mov_b32_e32 v218, v217
	v_cvt_pk_bf16_f32 v206, v98, v99
	v_pk_mul_f32 v[98:99], v[6:7], v[214:215]
	v_mov_b32_e32 v222, v221
	v_cvt_pk_bf16_f32 v207, v98, v99
	v_pk_mul_f32 v[98:99], v[0:1], v[218:219]
	v_add_u32_e32 v96, s38, v170
	v_cvt_pk_bf16_f32 v208, v98, v99
	v_pk_mul_f32 v[98:99], v[2:3], v[222:223]
	s_add_i32 s69, s66, 0xfffff501
	v_cvt_pk_bf16_f32 v209, v98, v99
	v_mad_i64_i32 v[98:99], s[50:51], s63, v96, 0
	v_lshl_add_u64 v[98:99], v[98:99], 1, v[152:153]
	v_lshl_add_u64 v[98:99], v[98:99], 0, s[48:49]
	v_lshl_add_u64 v[98:99], v[98:99], 0, v[156:157]
	global_store_dwordx4 v[98:99], v[206:209], off sc1
	s_waitcnt lgkmcnt(0)
	s_andn2_b64 vcc, exec, s[46:47]
	s_mov_b64 s[46:47], 0
	s_cbranch_vccnz .LBB0_584
	s_cmp_lt_i32 s69, s36
	s_cselect_b64 s[46:47], -1, 0
	s_cmp_ge_i32 s69, s36
	s_cbranch_scc1 .LBB0_583
	s_mul_hi_i32 s2, s69, 0xc0784b3
	s_lshr_b32 s30, s2, 31
	s_ashr_i32 s2, s2, 10
	s_add_i32 s50, s2, s30
	s_mul_i32 s2, s50, 0xffffaae0
	s_add_i32 s71, s66, s2
	s_add_i32 s70, s71, 0xfffff501
	s_cmpk_lt_i32 s70, 0x3420
	s_cselect_b64 s[54:55], -1, 0
	s_add_i32 s2, s71, 0xffffc0e1
	s_cmpk_gt_i32 s70, 0x341f
	s_cselect_b64 s[56:57], -1, 0
	s_and_b64 s[30:31], s[56:57], exec
	s_cselect_b32 s45, s2, s70
	s_cmpk_gt_i32 s45, 0x20ff
	s_mov_b64 s[58:59], -1
	s_cbranch_scc0 .LBB0_628
	s_ashr_i32 s51, s50, 31
	s_cmpk_gt_u32 s45, 0x301f
	s_mov_b64 s[52:53], -1
	s_cbranch_scc0 .LBB0_626
	s_load_dwordx2 s[30:31], s[0:1], 0x38
	s_lshl_b64 s[48:49], s[50:51], 24
	s_waitcnt lgkmcnt(0)
	s_add_u32 s48, s30, s48
	s_addc_u32 s49, s31, s49
	s_lshl_b32 s2, s45, 1
	s_lshl_b32 s30, s45, 6
	s_andn2_b32 s2, s2, 63
	s_and_b32 s72, s30, 0x7c0
	s_add_i32 s30, s2, 0xffff9fc0
	s_lshl_b64 s[52:53], s[50:51], 23
	s_add_u32 s60, s39, s52
	s_addc_u32 s61, s62, s53
	s_mov_b64 s[52:53], 0

; #define GAS __attribute__((address_space(1)))
; #define LAS __attribute__((address_space(3)))
; #define LDS_WAIT() asm volatile("s_waitcnt lgkmcnt(0)" ::: "memory")
; DI unsigned pk2(float lo, float hi) { f32x2 v = {lo, hi}; bf16x2_t b = __builtin_convertvector(v, bf16x2_t); return __builtin_bit_cast(unsigned, b); }
;     ...
;         LAS float* w = scr + (lane >> 4) * 65 + 4 * (lane & 15);
; #pragma unroll
;         for (int i = 0; i < 16; ++i) { w[(4 * i) * 65 + 0] = v[i].x; w[(4 * i) * 65 + 1] = v[i].y; w[(4 * i) * 65 + 2] = v[i].z; w[(4 * i) * 65 + 3] = v[i].w; }
;     }
;     LDS_WAIT(); asm volatile("" ::: "memory");
;     const int c = lane & 7;
;     const f32x4 s0 = sc[0], s1 = sc[1];
; #pragma unroll
;     for (int j = 0; j < 8; ++j) {
;         const int nn = (lane >> 3) + 8 * j; const LAS float* s = scr + (8 * c) * 65 + nn;
;         v4u o; o.x = pk2(s[0 * 65] * s0.x, s[1 * 65] * s0.y); o.y = pk2(s[2 * 65] * s0.z, s[3 * 65] * s0.w); o.z = pk2(s[4 * 65] * s1.x, s[5 * 65] * s1.y); o.w = pk2(s[6 * 65] * s1.z, s[7 * 65] * s1.w);
;         if (!(variant & 4)) *(GAS v4u*)(t.dst + (size_t)(t.drow0 + nn) * t.Kd + t.k0 + 8 * c) = o;
;         else asm volatile("" :: "v"(o));
;     }
;     LDS_WAIT(); asm volatile("" ::: "memory");
.LBB0_1096:
	v_add_u32_e32 v172, 0x410, v161
	v_add_u32_e32 v173, 0x418, v161
	v_add_u32_e32 v174, 0x820, v161
	v_add_u32_e32 v175, 0x828, v161
	v_add_u32_e32 v176, 0xc30, v161
	v_add_u32_e32 v177, 0xc38, v161
	v_add_u32_e32 v178, 0x1040, v161
	v_add_u32_e32 v179, 0x1048, v161
	v_add_u32_e32 v180, 0x1450, v161
	v_add_u32_e32 v181, 0x1458, v161
	v_add_u32_e32 v186, 0x1860, v161
	v_add_u32_e32 v187, 0x1868, v161
	v_add_u32_e32 v188, 0x1c70, v161
	v_add_u32_e32 v189, 0x1c78, v161
	v_add_u32_e32 v190, 0x2080, v161
	v_add_u32_e32 v191, 0x2088, v161
	v_add_u32_e32 v192, 0x2490, v161
	v_add_u32_e32 v193, 0x2498, v161
	v_add_u32_e32 v194, 0x28a0, v161
	v_add_u32_e32 v195, 0x28a8, v161
	v_add_u32_e32 v196, 0x2cb0, v161
	v_add_u32_e32 v197, 0x2cb8, v161
	v_add_u32_e32 v198, 0x30c0, v161
	v_add_u32_e32 v199, 0x30c8, v161
	v_add_u32_e32 v200, 0x34d0, v161
	v_add_u32_e32 v201, 0x34d8, v161
	v_add_u32_e32 v202, 0x38e0, v161
	v_add_u32_e32 v203, 0x38e8, v161
	v_add_u32_e32 v204, 0x3cf0, v161
	v_add_u32_e32 v205, 0x3cf8, v161
	s_waitcnt vmcnt(1)
	ds_write2_b32 v161, v8, v9 offset1:1
	ds_write2_b32 v161, v10, v11 offset0:2 offset1:3
	s_waitcnt vmcnt(0)
	ds_write2_b32 v172, v12, v13 offset1:1
	ds_write2_b32 v173, v14, v15 offset1:1
	ds_write2_b32 v174, v16, v17 offset1:1
	ds_write2_b32 v175, v18, v19 offset1:1
	ds_write2_b32 v176, v20, v21 offset1:1
	ds_write2_b32 v177, v22, v23 offset1:1
	ds_write2_b32 v178, v24, v25 offset1:1
	ds_write2_b32 v179, v26, v27 offset1:1
	ds_write2_b32 v180, v28, v29 offset1:1
	ds_write2_b32 v181, v30, v31 offset1:1
	ds_write2_b32 v186, v32, v33 offset1:1
	ds_write2_b32 v187, v34, v35 offset1:1
	ds_write2_b32 v188, v36, v37 offset1:1
	ds_write2_b32 v189, v38, v39 offset1:1
	ds_write2_b32 v190, v40, v41 offset1:1
	ds_write2_b32 v191, v42, v43 offset1:1
	ds_write2_b32 v192, v44, v45 offset1:1
	ds_write2_b32 v193, v46, v47 offset1:1
	ds_write2_b32 v194, v48, v49 offset1:1
	ds_write2_b32 v195, v50, v51 offset1:1
	ds_write2_b32 v196, v52, v53 offset1:1
	ds_write2_b32 v197, v54, v55 offset1:1
	ds_write2_b32 v198, v64, v65 offset1:1
	ds_write2_b32 v199, v66, v67 offset1:1
	ds_write2_b32 v200, v68, v69 offset1:1
	ds_write2_b32 v201, v70, v71 offset1:1
	ds_write2_b32 v202, v72, v73 offset1:1
	ds_write2_b32 v203, v74, v75 offset1:1
	ds_write2_b32 v204, v80, v81 offset1:1
	ds_write2_b32 v205, v82, v83 offset1:1
	s_waitcnt lgkmcnt(0)
	ds_read2_b32 v[98:99], v163 offset1:8
	ds_read2_b32 v[102:103], v163 offset0:65 offset1:73
	ds_read2_b32 v[210:211], v163 offset0:130 offset1:138
	ds_read2_b32 v[212:213], v163 offset0:195 offset1:203
	v_add_u32_e32 v171, 0x400, v163
	ds_read2_b32 v[214:215], v171 offset0:4 offset1:12
	ds_read2_b32 v[216:217], v171 offset0:69 offset1:77
	ds_read2_b32 v[218:219], v171 offset0:134 offset1:142
	ds_read2_b32 v[220:221], v171 offset0:199 offset1:207
	s_waitcnt lgkmcnt(7)
	v_mov_b32_e32 v206, v98
	s_waitcnt lgkmcnt(6)
	v_mov_b32_e32 v207, v102
	s_waitcnt lgkmcnt(5)
	v_mov_b32_e32 v208, v210
	s_waitcnt lgkmcnt(4)
	v_mov_b32_e32 v209, v212
	v_pk_mul_f32 v[206:207], v[4:5], v[206:207]
	v_pk_mul_f32 v[208:209], v[6:7], v[208:209]
	v_cvt_pk_bf16_f32 v206, v206, v207
	v_cvt_pk_bf16_f32 v207, v208, v209
	s_waitcnt lgkmcnt(3)
	v_mov_b32_e32 v208, v214
	s_waitcnt lgkmcnt(2)
	v_mov_b32_e32 v209, v216
	s_waitcnt lgkmcnt(1)
	v_mov_b32_e32 v222, v218
	s_waitcnt lgkmcnt(0)
	v_mov_b32_e32 v223, v220
	v_pk_mul_f32 v[208:209], v[0:1], v[208:209]
	v_pk_mul_f32 v[222:223], v[2:3], v[222:223]
	v_add_u32_e32 v96, s38, v162
	v_cvt_pk_bf16_f32 v208, v208, v209
	v_cvt_pk_bf16_f32 v209, v222, v223
	v_mad_i64_i32 v[222:223], s[48:49], s63, v96, 0
	s_ashr_i32 s31, s30, 31
	v_lshl_add_u64 v[222:223], v[222:223], 1, v[152:153]
	s_lshl_b64 s[48:49], s[30:31], 1
	v_lshl_add_u64 v[222:223], v[222:223], 0, s[48:49]
	v_mov_b32_e32 v157, v97
	v_mov_b32_e32 v102, v99
	v_lshl_add_u64 v[222:223], v[222:223], 0, v[156:157]
	v_pk_mul_f32 v[98:99], v[4:5], v[102:103]
	v_mov_b32_e32 v212, v211
	global_store_dwordx4 v[222:223], v[206:209], off sc1
	v_mov_b32_e32 v216, v215
	v_mov_b32_e32 v220, v219
	v_cvt_pk_bf16_f32 v206, v98, v99
	v_pk_mul_f32 v[98:99], v[6:7], v[212:213]
	v_add_u32_e32 v96, s38, v164
	v_cvt_pk_bf16_f32 v207, v98, v99
	v_pk_mul_f32 v[98:99], v[0:1], v[216:217]
	ds_read2_b32 v[102:103], v163 offset0:16 offset1:24
	v_cvt_pk_bf16_f32 v208, v98, v99
	v_pk_mul_f32 v[98:99], v[2:3], v[220:221]
	ds_read2_b32 v[210:211], v163 offset0:81 offset1:89
	v_cvt_pk_bf16_f32 v209, v98, v99
	v_mad_i64_i32 v[98:99], s[50:51], s63, v96, 0
	v_lshl_add_u64 v[98:99], v[98:99], 1, v[152:153]
	ds_read2_b32 v[212:213], v163 offset0:146 offset1:154
	ds_read2_b32 v[214:215], v163 offset0:211 offset1:219
	v_lshl_add_u64 v[98:99], v[98:99], 0, s[48:49]
	v_lshl_add_u64 v[98:99], v[98:99], 0, v[156:157]
	ds_read2_b32 v[216:217], v171 offset0:20 offset1:28
	ds_read2_b32 v[218:219], v171 offset0:85 offset1:93
	global_store_dwordx4 v[98:99], v[206:209], off sc1
	s_waitcnt lgkmcnt(5)
	v_mov_b32_e32 v98, v102
	s_waitcnt lgkmcnt(4)
	v_mov_b32_e32 v99, v210
	v_pk_mul_f32 v[98:99], v[4:5], v[98:99]
	ds_read2_b32 v[220:221], v171 offset0:150 offset1:158
	ds_read2_b32 v[222:223], v171 offset0:215 offset1:223
	v_cvt_pk_bf16_f32 v206, v98, v99
	s_waitcnt lgkmcnt(5)
	v_mov_b32_e32 v98, v212
	s_waitcnt lgkmcnt(4)
	v_mov_b32_e32 v99, v214
	v_pk_mul_f32 v[98:99], v[6:7], v[98:99]
	v_add_u32_e32 v96, s38, v165
	v_cvt_pk_bf16_f32 v207, v98, v99
	s_waitcnt lgkmcnt(3)
	v_mov_b32_e32 v98, v216
	s_waitcnt lgkmcnt(2)
	v_mov_b32_e32 v99, v218
	v_pk_mul_f32 v[98:99], v[0:1], v[98:99]
	v_mov_b32_e32 v210, v103
	v_cvt_pk_bf16_f32 v208, v98, v99
	s_waitcnt lgkmcnt(1)
	v_mov_b32_e32 v98, v220
	s_waitcnt lgkmcnt(0)
; #define GAS __attribute__((address_space(1)))
; #define LAS __attribute__((address_space(3)))
; #define LDS_WAIT() asm volatile("s_waitcnt lgkmcnt(0)" ::: "memory")
; DI unsigned pk2(float lo, float hi) { f32x2 v = {lo, hi}; bf16x2_t b = __builtin_convertvector(v, bf16x2_t); return __builtin_bit_cast(unsigned, b); }
; DI void tr_decode(const Frame& F, int git, TrItem& t) {
;     const int l = git / I_LAYER; int r = git - l * I_LAYER;
;     int s = 0;
;     if (r >= 3 * I_G + I_IN + I_OUT) { s = 1; r -= 3 * I_G + I_IN + I_OUT; }
;     if (r < 3 * I_G) {
;         const int kind = r / I_G; r -= kind * I_G; const int f = 2 * l + s;
;         if (kind < 2) {
;             const int up = kind;
;             t.W = F.in[s ? (up ? 21 : 20) : (up ? 3 : 2)] + (size_t)l * D * DFF; t.sc = F.in[s ? 19 : 1] + l * D;
;             const int kb = r / (DFF / 64), nb = r % (DFF / 64); t.k0 = 64 * kb; t.n0 = 64 * nb; t.N = DFF; t.Kd = D;
;             t.dst = (bf16*)(F.ws + WS_WGU + (size_t)f * SZ_WGU1); t.drow0 = 256 * (t.n0 >> 7) + (t.n0 & 127) + (up ? 128 : 0);
;         } else {
;             t.W = F.in[s ? 22 : 4] + (size_t)l * DFF * D; t.sc = nullptr;
;             const int kb = r / (D / 64), nb = r % (D / 64); t.k0 = 64 * kb; t.n0 = 64 * nb; t.N = D; t.Kd = DFF;
;             t.dst = (bf16*)(F.ws + WS_WD + (size_t)f * SZ_WD1); t.drow0 = t.n0;
;         }
;         return;
;     }
;     r -= 3 * I_G;
;     if (r < I_IN) {
;         t.W = F.in[6] + (size_t)l * D * DIN; t.sc = F.in[5] + l * D;
;         const int kb = r / 121, nb = r % 121; t.k0 = 64 * kb; t.n0 = 64 * nb; t.N = DIN; t.Kd = D;
;         t.dst = (bf16*)(F.ws + WS_WIN + (size_t)l * SZ_WIN1); t.drow0 = t.n0;
;         return;
;     }
;     r -= I_IN;
;     ...
;     for (int j = 0; j < 8; ++j) {
;         const int nn = (lane >> 3) + 8 * j; const LAS float* s = scr + (8 * c) * 65 + nn;
;         v4u o; o.x = pk2(s[0 * 65] * s0.x, s[1 * 65] * s0.y); o.y = pk2(s[2 * 65] * s0.z, s[3 * 65] * s0.w); o.z = pk2(s[4 * 65] * s1.x, s[5 * 65] * s1.y); o.w = pk2(s[6 * 65] * s1.z, s[7 * 65] * s1.w);
;         if (!(variant & 4)) *(GAS v4u*)(t.dst + (size_t)(t.drow0 + nn) * t.Kd + t.k0 + 8 * c) = o;
;         else asm volatile("" :: "v"(o));
;     }
;     LDS_WAIT(); asm volatile("" ::: "memory");
	v_mov_b32_e32 v99, v222
	v_pk_mul_f32 v[98:99], v[2:3], v[98:99]
	v_mov_b32_e32 v214, v213
	v_cvt_pk_bf16_f32 v209, v98, v99
	v_mad_i64_i32 v[98:99], s[50:51], s63, v96, 0
	v_lshl_add_u64 v[98:99], v[98:99], 1, v[152:153]
	v_lshl_add_u64 v[98:99], v[98:99], 0, s[48:49]
	v_lshl_add_u64 v[98:99], v[98:99], 0, v[156:157]
	global_store_dwordx4 v[98:99], v[206:209], off sc1
	v_pk_mul_f32 v[98:99], v[4:5], v[210:211]
	v_mov_b32_e32 v218, v217
	v_cvt_pk_bf16_f32 v206, v98, v99
	v_pk_mul_f32 v[98:99], v[6:7], v[214:215]
	v_mov_b32_e32 v222, v221
	v_cvt_pk_bf16_f32 v207, v98, v99
	v_pk_mul_f32 v[98:99], v[0:1], v[218:219]
	v_add_u32_e32 v96, s38, v166
	v_cvt_pk_bf16_f32 v208, v98, v99
	v_pk_mul_f32 v[98:99], v[2:3], v[222:223]
	ds_read2_b32 v[102:103], v163 offset0:32 offset1:40
	ds_read2_b32 v[210:211], v163 offset0:97 offset1:105
	v_cvt_pk_bf16_f32 v209, v98, v99
	v_mad_i64_i32 v[98:99], s[50:51], s63, v96, 0
	v_lshl_add_u64 v[98:99], v[98:99], 1, v[152:153]
	ds_read2_b32 v[212:213], v163 offset0:162 offset1:170
	ds_read2_b32 v[214:215], v163 offset0:227 offset1:235
	v_lshl_add_u64 v[98:99], v[98:99], 0, s[48:49]
	v_lshl_add_u64 v[98:99], v[98:99], 0, v[156:157]
	ds_read2_b32 v[216:217], v171 offset0:36 offset1:44
	ds_read2_b32 v[218:219], v171 offset0:101 offset1:109
	global_store_dwordx4 v[98:99], v[206:209], off sc1
	s_waitcnt lgkmcnt(5)
	v_mov_b32_e32 v98, v102
	s_waitcnt lgkmcnt(4)
	v_mov_b32_e32 v99, v210
	v_pk_mul_f32 v[98:99], v[4:5], v[98:99]
	ds_read2_b32 v[220:221], v171 offset0:166 offset1:174
	ds_read2_b32 v[222:223], v171 offset0:231 offset1:239
	v_cvt_pk_bf16_f32 v206, v98, v99
	s_waitcnt lgkmcnt(5)
	v_mov_b32_e32 v98, v212
	s_waitcnt lgkmcnt(4)
	v_mov_b32_e32 v99, v214
	v_pk_mul_f32 v[98:99], v[6:7], v[98:99]
	v_add_u32_e32 v96, s38, v167
	v_cvt_pk_bf16_f32 v207, v98, v99
	s_waitcnt lgkmcnt(3)
	v_mov_b32_e32 v98, v216
	s_waitcnt lgkmcnt(2)
	v_mov_b32_e32 v99, v218
	v_pk_mul_f32 v[98:99], v[0:1], v[98:99]
	v_mov_b32_e32 v210, v103
	v_cvt_pk_bf16_f32 v208, v98, v99
	s_waitcnt lgkmcnt(1)
	v_mov_b32_e32 v98, v220
	s_waitcnt lgkmcnt(0)
	v_mov_b32_e32 v99, v222
	v_pk_mul_f32 v[98:99], v[2:3], v[98:99]
	v_mov_b32_e32 v214, v213
	v_cvt_pk_bf16_f32 v209, v98, v99
	v_mad_i64_i32 v[98:99], s[50:51], s63, v96, 0
	v_lshl_add_u64 v[98:99], v[98:99], 1, v[152:153]
	v_lshl_add_u64 v[98:99], v[98:99], 0, s[48:49]
	v_lshl_add_u64 v[98:99], v[98:99], 0, v[156:157]
	global_store_dwordx4 v[98:99], v[206:209], off sc1
	v_pk_mul_f32 v[98:99], v[4:5], v[210:211]
	v_mov_b32_e32 v218, v217
	v_cvt_pk_bf16_f32 v206, v98, v99
	v_pk_mul_f32 v[98:99], v[6:7], v[214:215]
	v_mov_b32_e32 v222, v221
	v_cvt_pk_bf16_f32 v207, v98, v99
	v_pk_mul_f32 v[98:99], v[0:1], v[218:219]
	v_add_u32_e32 v96, s38, v168
	v_cvt_pk_bf16_f32 v208, v98, v99
	v_pk_mul_f32 v[98:99], v[2:3], v[222:223]
	ds_read2_b32 v[102:103], v163 offset0:48 offset1:56
	ds_read2_b32 v[210:211], v163 offset0:113 offset1:121
	v_cvt_pk_bf16_f32 v209, v98, v99
	v_mad_i64_i32 v[98:99], s[50:51], s63, v96, 0
	v_lshl_add_u64 v[98:99], v[98:99], 1, v[152:153]
	ds_read2_b32 v[212:213], v163 offset0:178 offset1:186
	ds_read2_b32 v[214:215], v163 offset0:243 offset1:251
	v_lshl_add_u64 v[98:99], v[98:99], 0, s[48:49]
	v_lshl_add_u64 v[98:99], v[98:99], 0, v[156:157]
	ds_read2_b32 v[216:217], v171 offset0:52 offset1:60
	ds_read2_b32 v[218:219], v171 offset0:117 offset1:125
	global_store_dwordx4 v[98:99], v[206:209], off sc1
	s_waitcnt lgkmcnt(5)
	v_mov_b32_e32 v98, v102
	s_waitcnt lgkmcnt(4)
	v_mov_b32_e32 v99, v210
	v_pk_mul_f32 v[98:99], v[4:5], v[98:99]
	ds_read2_b32 v[220:221], v171 offset0:182 offset1:190
	ds_read2_b32 v[222:223], v171 offset0:247 offset1:255
	v_cvt_pk_bf16_f32 v206, v98, v99
	s_waitcnt lgkmcnt(5)
	v_mov_b32_e32 v98, v212
	s_waitcnt lgkmcnt(4)
	v_mov_b32_e32 v99, v214
	v_pk_mul_f32 v[98:99], v[6:7], v[98:99]
	v_add_u32_e32 v96, s38, v169
	v_cvt_pk_bf16_f32 v207, v98, v99
	s_waitcnt lgkmcnt(3)
	v_mov_b32_e32 v98, v216
	s_waitcnt lgkmcnt(2)
	v_mov_b32_e32 v99, v218
	v_pk_mul_f32 v[98:99], v[0:1], v[98:99]
	v_mov_b32_e32 v210, v103
	v_cvt_pk_bf16_f32 v208, v98, v99
	s_waitcnt lgkmcnt(1)
	v_mov_b32_e32 v98, v220
	s_waitcnt lgkmcnt(0)
	v_mov_b32_e32 v99, v222
	v_pk_mul_f32 v[98:99], v[2:3], v[98:99]
	v_mov_b32_e32 v214, v213
	v_cvt_pk_bf16_f32 v209, v98, v99
	v_mad_i64_i32 v[98:99], s[50:51], s63, v96, 0
	v_lshl_add_u64 v[98:99], v[98:99], 1, v[152:153]
	v_lshl_add_u64 v[98:99], v[98:99], 0, s[48:49]
	v_lshl_add_u64 v[98:99], v[98:99], 0, v[156:157]
	global_store_dwordx4 v[98:99], v[206:209], off sc1
	v_pk_mul_f32 v[98:99], v[4:5], v[210:211]
	v_mov_b32_e32 v218, v217
	v_cvt_pk_bf16_f32 v206, v98, v99
	v_pk_mul_f32 v[98:99], v[6:7], v[214:215]
	v_mov_b32_e32 v222, v221
	v_cvt_pk_bf16_f32 v207, v98, v99
	v_pk_mul_f32 v[98:99], v[0:1], v[218:219]
	v_add_u32_e32 v96, s38, v170
	v_cvt_pk_bf16_f32 v208, v98, v99
	v_pk_mul_f32 v[98:99], v[2:3], v[222:223]
	s_add_i32 s69, s66, 0xfffff501
	v_cvt_pk_bf16_f32 v209, v98, v99
	v_mad_i64_i32 v[98:99], s[50:51], s63, v96, 0
	v_lshl_add_u64 v[98:99], v[98:99], 1, v[152:153]
	v_lshl_add_u64 v[98:99], v[98:99], 0, s[48:49]
	v_lshl_add_u64 v[98:99], v[98:99], 0, v[156:157]
	global_store_dwordx4 v[98:99], v[206:209], off sc1
	s_waitcnt lgkmcnt(0)
	s_andn2_b64 vcc, exec, s[46:47]
	s_mov_b64 s[46:47], 0
	s_cbranch_vccnz .LBB0_1059
	s_cmp_lt_i32 s69, s36
	s_cselect_b64 s[46:47], -1, 0
	s_cmp_ge_i32 s69, s36
	s_cbranch_scc1 .LBB0_1058
	s_mul_hi_i32 s2, s69, 0xc0784b3
	s_lshr_b32 s30, s2, 31
	s_ashr_i32 s2, s2, 10
	s_add_i32 s50, s2, s30
	s_mul_i32 s2, s50, 0xffffaae0
	s_add_i32 s71, s66, s2
	s_add_i32 s70, s71, 0xfffff501
	s_cmpk_lt_i32 s70, 0x3420
	s_cselect_b64 s[54:55], -1, 0
	s_add_i32 s2, s71, 0xffffc0e1
	s_cmpk_gt_i32 s70, 0x341f
	s_cselect_b64 s[56:57], -1, 0
	s_and_b64 s[30:31], s[56:57], exec
	s_cselect_b32 s45, s2, s70
	s_cmpk_gt_i32 s45, 0x20ff
	s_mov_b64 s[58:59], -1
	s_cbranch_scc0 .LBB0_1103
	s_ashr_i32 s51, s50, 31
	s_cmpk_gt_u32 s45, 0x301f
	s_mov_b64 s[52:53], -1
	s_cbranch_scc0 .LBB0_1101
	s_load_dwordx2 s[30:31], s[0:1], 0x38
	s_lshl_b64 s[48:49], s[50:51], 24
	s_waitcnt lgkmcnt(0)
	s_add_u32 s48, s30, s48
	s_addc_u32 s49, s31, s49
	s_lshl_b32 s2, s45, 1
	s_lshl_b32 s30, s45, 6
	s_andn2_b32 s2, s2, 63
	s_and_b32 s72, s30, 0x7c0
	s_add_i32 s30, s2, 0xffff9fc0
	s_lshl_b64 s[52:53], s[50:51], 23
	s_add_u32 s60, s39, s52
	s_addc_u32 s61, s62, s53
	s_mov_b64 s[52:53], 0
